# asm-guide 7.12: per-tile rescale test chain shortened (redundant canonicalizing v_max pairs dropped, row-max tail + carry mov hoisted above the tile's last MFMA) in A/B/C loops
# speedup vs baseline: 1.0017x; 1.0017x over previous
; DI float max3f(float a, float b, float c) { float r; asm("v_max3_f32 %0, %1, %2, %3" : "=v"(r) : "v"(a), "v"(b), "v"(c)); return r; }
; DI float swapmax(float m) { auto rr = __builtin_amdgcn_permlane32_swap(__float_as_uint(m), __float_as_uint(m), false, false); return fmaxf(__uint_as_float(rr[0]), __uint_as_float(rr[1])); }
; #define SBAR() __builtin_amdgcn_sched_barrier(0)
; #define MF(a_, b_, c_) __builtin_amdgcn_mfma_f32_32x32x16_bf16(a_, b_, c_, 0, 0, 0)
; #define ATT_KLD(so_, h_) do { const lds_cptr kb_ = shm3 + (so_) + ((KIND == 0) ? m * 8192 : 0) + hi * 1024 + r32 * 16 + (h_) * 4096; \
;         kf[0] = *(const LAS bf16x8*)(kb_); kf[1] = *(const LAS bf16x8*)(kb_ + 512); kf[2] = *(const LAS bf16x8*)(kb_ + 2048); kf[3] = *(const LAS bf16x8*)(kb_ + 2560); } while (0)
; #define ATT_XLD(so_) do { if (KIND == 2) { const lds_cptr xb_ = shm3 + (so_) + 32768 + r32 * 16; x0 = *(const LAS bf16x8*)(xb_); x1 = *(const LAS bf16x8*)(xb_ + 512); if (hi) { x0 = (bf16x8){0, 0, 0, 0, 0, 0, 0, 0}; x1 = x0; } } } while (0)
; template <int KIND> DI void attn_unit(const Params& P, int b, int h, int qb, char* shm, float lam, bool dry = false) {
;     ...
;     f32x16 pa0, pa1, pb0, pb1;
;     bf16x8 kf[4], x0, x1;
;     ATT_KLD(0, 0); ATT_XLD(0);
;     pa0 = MF(kf[0], qr[0], negm); pa1 = MF(kf[1], qr[0], negm); pa0 = MF(kf[2], qr[1], pa0); pa1 = MF(kf[3], qr[1], pa1);
;     SBAR(); ATT_KLD(0, 1); SBAR();
;     pa0 = MF(kf[0], qr[2], pa0); pa1 = MF(kf[1], qr[2], pa1); pa0 = MF(kf[2], qr[3], pa0); pa1 = MF(kf[3], qr[3], pa1);
;     if (KIND == 2) { pa0 = MF(x0, ones, pa0); pa1 = MF(x1, ones, pa1); }
;     ATT_FIX(pa0, pa1, ATT_TILE(0));
;     { float rm = max3f(pa0[0], pa0[1], pa1[0]), rm2 = max3f(pa0[2], pa0[3], pa1[1]); rm = max3f(rm, pa1[2], pa1[3]);
; #pragma unroll
;       for (int r = 4; r < 16; r += 4) { rm = max3f(rm, pa0[r], pa0[r + 1]); rm2 = max3f(rm2, pa0[r + 2], pa0[r + 3]); rm = max3f(rm, pa1[r], pa1[r + 1]); rm2 = max3f(rm2, pa1[r + 2], pa1[r + 3]); }
;       rm = swapmax(max3f(rm, rm2, rm2)); ATT_DECIDE(pa0, pa1, rm); }
.LBB0_337:
	s_cmp_lt_i32 s18, 3
	s_cselect_b64 vcc, -1, 0
	s_nop 6
	v_cndmask_b32_e32 v4, v4, v245, vcc
	v_cndmask_b32_e32 v69, v21, v245, vcc
	v_cndmask_b32_e32 v68, v20, v245, vcc
	v_max3_f32 v20, v68, v69, v4
	v_cndmask_b32_e32 v7, v7, v245, vcc
	v_cndmask_b32_e32 v6, v6, v245, vcc
	v_cndmask_b32_e32 v5, v5, v245, vcc
	v_cndmask_b32_e32 v71, v23, v245, vcc
	v_cndmask_b32_e32 v70, v22, v245, vcc
	v_max3_f32 v21, v70, v71, v5
	v_max3_f32 v20, v20, v6, v7
	v_cndmask_b32_e32 v75, v27, v245, vcc
	v_cndmask_b32_e32 v74, v26, v245, vcc
	v_cndmask_b32_e32 v73, v25, v245, vcc
	v_cndmask_b32_e32 v72, v24, v245, vcc
	v_max3_f32 v20, v20, v72, v73
	v_max3_f32 v21, v21, v74, v75
	v_cndmask_b32_e32 v11, v11, v245, vcc
	v_cndmask_b32_e32 v10, v10, v245, vcc
	v_cndmask_b32_e32 v9, v9, v245, vcc
	v_cndmask_b32_e32 v8, v8, v245, vcc
	v_max3_f32 v20, v20, v8, v9
	v_max3_f32 v21, v21, v10, v11
	v_cndmask_b32_e32 v79, v31, v245, vcc
	v_cndmask_b32_e32 v78, v30, v245, vcc
	v_cndmask_b32_e32 v77, v29, v245, vcc
	v_cndmask_b32_e32 v76, v28, v245, vcc
	v_max3_f32 v20, v20, v76, v77
	v_max3_f32 v21, v21, v78, v79
	v_cndmask_b32_e32 v15, v15, v245, vcc
	v_cndmask_b32_e32 v14, v14, v245, vcc
	v_cndmask_b32_e32 v13, v13, v245, vcc
	v_cndmask_b32_e32 v12, v12, v245, vcc
	v_max3_f32 v20, v20, v12, v13
	v_max3_f32 v21, v21, v14, v15
	v_cndmask_b32_e32 v83, v35, v245, vcc
	v_cndmask_b32_e32 v82, v34, v245, vcc
	v_cndmask_b32_e32 v81, v33, v245, vcc
	v_cndmask_b32_e32 v80, v32, v245, vcc
	v_max3_f32 v20, v20, v80, v81
	v_max3_f32 v21, v21, v82, v83
	v_cndmask_b32_e32 v19, v19, v245, vcc
	v_cndmask_b32_e32 v18, v18, v245, vcc
	v_cndmask_b32_e32 v17, v17, v245, vcc
	v_cndmask_b32_e32 v16, v16, v245, vcc
	v_max3_f32 v20, v20, v16, v17
	v_max3_f32 v21, v21, v18, v19
	v_writelane_b32 v255, s15, 51
	v_max3_f32 v20, v20, v21, v21
	s_mov_b32 s3, 0x40c00000
	v_mov_b32_e32 v21, v20
	s_nop 1
	v_permlane32_swap_b32_e32 v20, v21


	v_max_f32_e32 v20, v20, v21
	v_cmp_lt_f32_e32 vcc, s88, v20
	v_writelane_b32 v255, s16, 52
	s_cbranch_vccz .LBB0_339
	v_max_f32_e32 v20, v20, v20
	v_max_f32_e32 v21, 0, v20
	v_exp_f32_e64 v22, -v21
	v_sub_f32_e32 v20, v36, v21
	v_add_f32_e32 v165, 0, v21
	v_sub_f32_e32 v83, v83, v21
	v_mul_f32_e32 v169, 0, v22
	v_sub_f32_e32 v82, v82, v21
	v_sub_f32_e32 v81, v81, v21
	v_sub_f32_e32 v80, v80, v21
	v_sub_f32_e32 v79, v79, v21
	v_sub_f32_e32 v78, v78, v21
	v_sub_f32_e32 v77, v77, v21
	v_sub_f32_e32 v76, v76, v21
	v_sub_f32_e32 v75, v75, v21
	v_sub_f32_e32 v74, v74, v21
	v_sub_f32_e32 v73, v73, v21
	v_sub_f32_e32 v72, v72, v21
	v_sub_f32_e32 v71, v71, v21
	v_sub_f32_e32 v70, v70, v21
	v_sub_f32_e32 v69, v69, v21
	v_sub_f32_e32 v68, v68, v21
	v_sub_f32_e32 v19, v19, v21
	v_sub_f32_e32 v18, v18, v21
	v_sub_f32_e32 v17, v17, v21
	v_sub_f32_e32 v16, v16, v21
	v_sub_f32_e32 v15, v15, v21
	v_sub_f32_e32 v14, v14, v21
	v_sub_f32_e32 v13, v13, v21
	v_sub_f32_e32 v12, v12, v21
	v_sub_f32_e32 v11, v11, v21
	v_sub_f32_e32 v10, v10, v21
	v_sub_f32_e32 v9, v9, v21
	v_sub_f32_e32 v8, v8, v21
	v_sub_f32_e32 v7, v7, v21
	v_sub_f32_e32 v6, v6, v21
	v_sub_f32_e32 v5, v5, v21
	v_sub_f32_e32 v4, v4, v21
	v_mov_b32_e32 v21, v20
	v_mov_b32_e32 v22, v20
	v_mov_b32_e32 v23, v20
	v_mov_b32_e32 v24, v20
	v_mov_b32_e32 v25, v20
	v_mov_b32_e32 v26, v20
	v_mov_b32_e32 v27, v20
	v_mov_b32_e32 v28, v20
	v_mov_b32_e32 v29, v20
	v_mov_b32_e32 v30, v20
	v_mov_b32_e32 v31, v20
	v_mov_b32_e32 v32, v20
	v_mov_b32_e32 v33, v20
	v_mov_b32_e32 v34, v20
	v_mov_b32_e32 v35, v20
	s_branch .LBB0_340

; DI float max3f(float a, float b, float c) { float r; asm("v_max3_f32 %0, %1, %2, %3" : "=v"(r) : "v"(a), "v"(b), "v"(c)); return r; }
; DI float swapmax(float m) { auto rr = __builtin_amdgcn_permlane32_swap(__float_as_uint(m), __float_as_uint(m), false, false); return fmaxf(__uint_as_float(rr[0]), __uint_as_float(rr[1])); }
; #define SBAR() __builtin_amdgcn_sched_barrier(0)
; #define PIN(x) asm volatile("" : "+v"(x))
; #define LDV(j_) do { if ((j_) < 4 * NDB) { const lds_cptr a_ = vp + ((j_) % NDB) * 4096 + ((j_) / NDB) * 1024; const s16x4 lo_ = vtr(a_), hi_ = vtr(a_ + 512); \
;             vq[(j_) & 3] = (bf16x8){lo_[0], lo_[1], lo_[2], lo_[3], hi_[0], hi_[1], hi_[2], hi_[3]}; } } while (0)
; #define PVM(j_) o[(j_) % NDB] = MF(vq[(j_) & 3], pw[(j_) / NDB], o[(j_) % NDB])
; template <int KIND> DI void attn_unit(const Params& P, int b, int h, int qb, char* shm, float lam, bool dry = false) {
;     ...
;             LDV(7); PVM(4); rm = max3f(pb0[0], pb0[1], pb1[0]); rm2 = max3f(pb0[2], pb0[3], pb1[1]); rm = max3f(rm, pb1[2], pb1[3]); rm2 = max3f(rm2, pb0[4], pb0[5]); PIN(rm); PIN(rm2); SBAR();
;             PVM(5); rm = max3f(rm, pb0[6], pb0[7]); rm2 = max3f(rm2, pb1[4], pb1[5]); rm = max3f(rm, pb1[6], pb1[7]); rm2 = max3f(rm2, pb0[8], pb0[9]); PIN(rm); PIN(rm2); SBAR();
;             PVM(6); rm = max3f(rm, pb0[10], pb0[11]); rm2 = max3f(rm2, pb1[8], pb1[9]); rm = max3f(rm, pb1[10], pb1[11]); rm2 = max3f(rm2, pb0[12], pb0[13]); PIN(rm); PIN(rm2); SBAR();
;             PVM(7); rm = max3f(rm, pb0[14], pb0[15]); rm2 = max3f(rm2, pb1[12], pb1[13]); rm = max3f(rm, pb1[14], pb1[15]); PIN(rm); PIN(rm2); SBAR();
;         }
;     ...
;         rm = swapmax(max3f(rm, rm2, rm2));
.Lct1_nomask:
	v_add_f32_e32 v169, v169, v68
	ds_read_b64_tr_b16 v[128:129], v164 offset:23552
	ds_read_b64_tr_b16 v[130:131], v164 offset:24064
	v_max3_f32 v116, v84, v85, v100
	v_max3_f32 v117, v86, v87, v101
	v_max3_f32 v116, v116, v102, v103
	v_max3_f32 v117, v117, v88, v89
	s_waitcnt lgkmcnt(4)
	v_mfma_f32_32x32x16_bf16 v[36:51], v[120:123], v[190:193], v[36:51]
	v_max3_f32 v116, v116, v90, v91
	v_max3_f32 v117, v117, v104, v105
	v_max3_f32 v116, v116, v106, v107
	v_max3_f32 v117, v117, v92, v93
	s_waitcnt lgkmcnt(2)
	v_mfma_f32_32x32x16_bf16 v[52:67], v[124:127], v[152:155], v[52:67]
	v_max3_f32 v116, v116, v94, v95
	v_max3_f32 v117, v117, v108, v109
	v_max3_f32 v116, v116, v110, v111
	v_max3_f32 v117, v117, v96, v97
	v_max3_f32 v116, v116, v98, v99
	v_max3_f32 v117, v117, v112, v113
	v_max3_f32 v116, v116, v114, v115
	v_max3_f32 v116, v116, v117, v117
	v_mov_b32_e32 v117, v116
	s_waitcnt lgkmcnt(0)
	v_mfma_f32_32x32x16_bf16 v[36:51], v[128:131], v[152:155], v[36:51]
	v_permlane32_swap_b32_e32 v116, v117
.LBB0_359:
	v_cmp_ge_i32_e64 s[18:19], s31, v173
	s_and_b64 vcc, exec, s[18:19]
	s_cbranch_vccnz .LBB0_362


; #define ATT_DECIDE(P0, P1, rm_) do { if (__any((rm_) > 6.0f)) { const float dl = fmaxf((rm_), 0.f); mhat += dl; const float f = EX(-dl); lsum *= f; \
;             _Pragma("unroll") for (int r = 0; r < 16; ++r) { P0[r] -= dl; P1[r] -= dl; negm[r] -= dl; } \
;             _Pragma("unroll") for (int i2 = 0; i2 < NDB; ++i2) _Pragma("unroll") for (int r = 0; r < 16; ++r) o[i2][r] *= f; } } while (0)
; template <int KIND> DI void attn_unit(const Params& P, int b, int h, int qb, char* shm, float lam, bool dry = false) {
;     ...
;         if (i + 1 < nt_eff) ATT_DECIDE(pb0, pb1, rm);
	v_max_f32_e32 v116, v116, v117
	v_cmp_lt_f32_e32 vcc, s3, v116
	s_cbranch_vccz .LBB0_362
	v_max_f32_e32 v116, v116, v116
	v_max_f32_e32 v117, 0, v116
	v_exp_f32_e64 v116, -v117
	v_add_f32_e32 v165, v165, v117
	v_sub_f32_e32 v99, v99, v117
	v_sub_f32_e32 v98, v98, v117
	v_pk_mul_f32 v[50:51], v[50:51], v[116:117] op_sel_hi:[1,0]
	v_pk_mul_f32 v[48:49], v[48:49], v[116:117] op_sel_hi:[1,0]
	v_pk_mul_f32 v[46:47], v[46:47], v[116:117] op_sel_hi:[1,0]
	v_pk_mul_f32 v[44:45], v[44:45], v[116:117] op_sel_hi:[1,0]
	v_pk_mul_f32 v[42:43], v[42:43], v[116:117] op_sel_hi:[1,0]
	v_pk_mul_f32 v[40:41], v[40:41], v[116:117] op_sel_hi:[1,0]
	v_pk_mul_f32 v[38:39], v[38:39], v[116:117] op_sel_hi:[1,0]
	v_pk_mul_f32 v[36:37], v[36:37], v[116:117] op_sel_hi:[1,0]
	v_pk_mul_f32 v[66:67], v[66:67], v[116:117] op_sel_hi:[1,0]
	v_pk_mul_f32 v[64:65], v[64:65], v[116:117] op_sel_hi:[1,0]
	v_pk_mul_f32 v[62:63], v[62:63], v[116:117] op_sel_hi:[1,0]
	v_pk_mul_f32 v[60:61], v[60:61], v[116:117] op_sel_hi:[1,0]
	v_pk_mul_f32 v[58:59], v[58:59], v[116:117] op_sel_hi:[1,0]
	v_pk_mul_f32 v[56:57], v[56:57], v[116:117] op_sel_hi:[1,0]
	v_pk_mul_f32 v[54:55], v[54:55], v[116:117] op_sel_hi:[1,0]
	v_pk_mul_f32 v[52:53], v[52:53], v[116:117] op_sel_hi:[1,0]
	v_sub_f32_e32 v97, v97, v117
	v_sub_f32_e32 v96, v96, v117
	v_sub_f32_e32 v95, v95, v117
	v_sub_f32_e32 v94, v94, v117
	v_sub_f32_e32 v93, v93, v117
	v_sub_f32_e32 v92, v92, v117
	v_sub_f32_e32 v91, v91, v117
	v_sub_f32_e32 v90, v90, v117
	v_sub_f32_e32 v89, v89, v117
	v_sub_f32_e32 v88, v88, v117
	v_sub_f32_e32 v87, v87, v117
	v_sub_f32_e32 v86, v86, v117
	v_sub_f32_e32 v85, v85, v117
	v_sub_f32_e32 v84, v84, v117
	v_sub_f32_e32 v115, v115, v117
	v_sub_f32_e32 v114, v114, v117
	v_sub_f32_e32 v113, v113, v117
	v_sub_f32_e32 v112, v112, v117
	v_sub_f32_e32 v111, v111, v117
	v_sub_f32_e32 v110, v110, v117
	v_sub_f32_e32 v109, v109, v117
	v_sub_f32_e32 v108, v108, v117
	v_sub_f32_e32 v107, v107, v117
	v_sub_f32_e32 v106, v106, v117
	v_sub_f32_e32 v105, v105, v117
	v_sub_f32_e32 v104, v104, v117
	v_sub_f32_e32 v103, v103, v117
	v_sub_f32_e32 v102, v102, v117
	v_sub_f32_e32 v101, v101, v117
	v_sub_f32_e32 v100, v100, v117
	v_sub_f32_e32 v35, v35, v117
	v_sub_f32_e32 v34, v34, v117
	v_sub_f32_e32 v33, v33, v117
	v_sub_f32_e32 v32, v32, v117
	v_sub_f32_e32 v31, v31, v117
	v_sub_f32_e32 v30, v30, v117
	v_sub_f32_e32 v29, v29, v117
	v_sub_f32_e32 v28, v28, v117
	v_sub_f32_e32 v27, v27, v117
	v_sub_f32_e32 v26, v26, v117
	v_sub_f32_e32 v25, v25, v117
	v_sub_f32_e32 v24, v24, v117
	v_sub_f32_e32 v23, v23, v117
	v_sub_f32_e32 v22, v22, v117
	v_sub_f32_e32 v21, v21, v117
	v_sub_f32_e32 v20, v20, v117
	v_mul_f32_e32 v169, v169, v116

; #define LAS __attribute__((address_space(3)))
; DI float max3f(float a, float b, float c) { float r; asm("v_max3_f32 %0, %1, %2, %3" : "=v"(r) : "v"(a), "v"(b), "v"(c)); return r; }
; DI float swapmax(float m) { auto rr = __builtin_amdgcn_permlane32_swap(__float_as_uint(m), __float_as_uint(m), false, false); return fmaxf(__uint_as_float(rr[0]), __uint_as_float(rr[1])); }
; DI float swapsum(float m) { auto rr = __builtin_amdgcn_permlane32_swap(__float_as_uint(m), __float_as_uint(m), false, false); return __uint_as_float(rr[0]) + __uint_as_float(rr[1]); }
; #define ATT_DECIDE(P0, P1, rm_) do { if (__any((rm_) > 6.0f)) { const float dl = fmaxf((rm_), 0.f); mhat += dl; const float f = EX(-dl); lsum *= f; \
;             _Pragma("unroll") for (int r = 0; r < 16; ++r) { P0[r] -= dl; P1[r] -= dl; negm[r] -= dl; } \
;             _Pragma("unroll") for (int i2 = 0; i2 < NDB; ++i2) _Pragma("unroll") for (int r = 0; r < 16; ++r) o[i2][r] *= f; } } while (0)
; template <int KIND> DI void attn_unit(const Params& P, int b, int h, int qb, char* shm, float lam, bool dry = false) {
;     ...
;         rm = swapmax(max3f(rm, rm2, rm2));
;         if (KIND == 2) {
;             const u32x2 kx = *(const LAS u32x2*)(shm3 + sc + 32768);
;             const float xk0 = __uint_as_float(kx.x << 16) + __uint_as_float(kx.x & 0xffff0000u) + __uint_as_float(kx.y << 16);
;             const float ltot = swapsum(lsum);
;             const bool ok = (qkmax + cb + xk0) < (mhat + __builtin_amdgcn_logf(ltot) - 54.0f);
;             const bool allok = __all(ok) && !(ATT_TILE(i) > wt_hi);
;             if (lane == 0) vote[8 * (i & 3) + wid] = allok ? 1u : 0u;
;         }
;         if (i + 1 < nt_eff) ATT_DECIDE(pb0, pb1, rm);
.Lct2_359:
	s_or_b64 exec, exec, s[38:39]
	v_cmp_ge_i32_e64 s[18:19], s31, v173
	s_and_b64 vcc, exec, s[18:19]
	s_cbranch_vccnz .Lct2_362


	v_max_f32_e32 v84, v84, v85
	v_cmp_lt_f32_e32 vcc, s3, v84
	s_cbranch_vccz .Lct2_362
	v_max_f32_e32 v84, v84, v84
	v_max_f32_e32 v85, 0, v84
	v_exp_f32_e64 v84, -v85
	v_add_f32_e32 v165, v165, v85
	v_sub_f32_e32 v131, v131, v85
	v_sub_f32_e32 v130, v130, v85
	v_pk_mul_f32 v[50:51], v[50:51], v[84:85] op_sel_hi:[1,0]
	v_pk_mul_f32 v[48:49], v[48:49], v[84:85] op_sel_hi:[1,0]
	v_pk_mul_f32 v[46:47], v[46:47], v[84:85] op_sel_hi:[1,0]
	v_pk_mul_f32 v[44:45], v[44:45], v[84:85] op_sel_hi:[1,0]
	v_pk_mul_f32 v[42:43], v[42:43], v[84:85] op_sel_hi:[1,0]
	v_pk_mul_f32 v[40:41], v[40:41], v[84:85] op_sel_hi:[1,0]
	v_pk_mul_f32 v[38:39], v[38:39], v[84:85] op_sel_hi:[1,0]
	v_pk_mul_f32 v[36:37], v[36:37], v[84:85] op_sel_hi:[1,0]
	v_pk_mul_f32 v[66:67], v[66:67], v[84:85] op_sel_hi:[1,0]
	v_pk_mul_f32 v[64:65], v[64:65], v[84:85] op_sel_hi:[1,0]
	v_pk_mul_f32 v[62:63], v[62:63], v[84:85] op_sel_hi:[1,0]
	v_pk_mul_f32 v[60:61], v[60:61], v[84:85] op_sel_hi:[1,0]
	v_pk_mul_f32 v[58:59], v[58:59], v[84:85] op_sel_hi:[1,0]
	v_pk_mul_f32 v[56:57], v[56:57], v[84:85] op_sel_hi:[1,0]
	v_pk_mul_f32 v[54:55], v[54:55], v[84:85] op_sel_hi:[1,0]
	v_pk_mul_f32 v[52:53], v[52:53], v[84:85] op_sel_hi:[1,0]
	v_sub_f32_e32 v129, v129, v85
	v_sub_f32_e32 v128, v128, v85
	v_sub_f32_e32 v127, v127, v85
	v_sub_f32_e32 v126, v126, v85
	v_sub_f32_e32 v125, v125, v85
	v_sub_f32_e32 v124, v124, v85
	v_sub_f32_e32 v123, v123, v85
	v_sub_f32_e32 v122, v122, v85
	v_sub_f32_e32 v121, v121, v85
	v_sub_f32_e32 v120, v120, v85
	v_sub_f32_e32 v119, v119, v85
	v_sub_f32_e32 v118, v118, v85
	v_sub_f32_e32 v117, v117, v85
	v_sub_f32_e32 v116, v116, v85
	v_sub_f32_e32 v19, v19, v85
	v_sub_f32_e32 v18, v18, v85
	v_sub_f32_e32 v17, v17, v85
	v_sub_f32_e32 v16, v16, v85
	v_sub_f32_e32 v15, v15, v85
	v_sub_f32_e32 v14, v14, v85
	v_sub_f32_e32 v13, v13, v85
	v_sub_f32_e32 v12, v12, v85
	v_sub_f32_e32 v11, v11, v85
	v_sub_f32_e32 v10, v10, v85
	v_sub_f32_e32 v9, v9, v85
	v_sub_f32_e32 v8, v8, v85
	v_sub_f32_e32 v7, v7, v85
	v_sub_f32_e32 v6, v6, v85
	v_sub_f32_e32 v5, v5, v85
	v_sub_f32_e32 v4, v4, v85
	v_sub_f32_e32 v35, v35, v85
	v_sub_f32_e32 v34, v34, v85
	v_sub_f32_e32 v33, v33, v85
	v_sub_f32_e32 v32, v32, v85
	v_sub_f32_e32 v31, v31, v85
	v_sub_f32_e32 v30, v30, v85
	v_sub_f32_e32 v29, v29, v85
	v_sub_f32_e32 v28, v28, v85
	v_sub_f32_e32 v27, v27, v85
	v_sub_f32_e32 v26, v26, v85
	v_sub_f32_e32 v25, v25, v85
	v_sub_f32_e32 v24, v24, v85
	v_sub_f32_e32 v23, v23, v85
	v_sub_f32_e32 v22, v22, v85
	v_sub_f32_e32 v21, v21, v85
	v_sub_f32_e32 v20, v20, v85
	v_mul_f32_e32 v169, v169, v84

; DI float max3f(float a, float b, float c) { float r; asm("v_max3_f32 %0, %1, %2, %3" : "=v"(r) : "v"(a), "v"(b), "v"(c)); return r; }
; DI float swapmax(float m) { auto rr = __builtin_amdgcn_permlane32_swap(__float_as_uint(m), __float_as_uint(m), false, false); return fmaxf(__uint_as_float(rr[0]), __uint_as_float(rr[1])); }
; #define SBAR() __builtin_amdgcn_sched_barrier(0)
; #define MF(a_, b_, c_) __builtin_amdgcn_mfma_f32_32x32x16_bf16(a_, b_, c_, 0, 0, 0)
; #define ATT_KLD(so_, h_) do { const lds_cptr kb_ = shm3 + (so_) + ((KIND == 0) ? m * 8192 : 0) + hi * 1024 + r32 * 16 + (h_) * 4096; \
;         kf[0] = *(const LAS bf16x8*)(kb_); kf[1] = *(const LAS bf16x8*)(kb_ + 512); kf[2] = *(const LAS bf16x8*)(kb_ + 2048); kf[3] = *(const LAS bf16x8*)(kb_ + 2560); } while (0)
; #define ATT_XLD(so_) do { if (KIND == 2) { const lds_cptr xb_ = shm3 + (so_) + 32768 + r32 * 16; x0 = *(const LAS bf16x8*)(xb_); x1 = *(const LAS bf16x8*)(xb_ + 512); if (hi) { x0 = (bf16x8){0, 0, 0, 0, 0, 0, 0, 0}; x1 = x0; } } } while (0)
; template <int KIND> DI void attn_unit(const Params& P, int b, int h, int qb, char* shm, float lam, bool dry = false) {
;     ...
;     else if (KIND == 1) { qrow0 = qb * 256 + 32 * wid; qoff = 512 + h * 64; const int cq = 4 * qb + (wid >> 1); T_lo = 4 * qb - 8 < 0 ? 0 : 4 * qb - 8; T_hi = 4 * qb + 3; wt_lo = cq - 8 < 0 ? 0 : cq - 8; wt_hi = cq; }
;     ...
;     f32x16 pa0, pa1, pb0, pb1;
;     bf16x8 kf[4], x0, x1;
;     ATT_KLD(0, 0); ATT_XLD(0);
;     pa0 = MF(kf[0], qr[0], negm); pa1 = MF(kf[1], qr[0], negm); pa0 = MF(kf[2], qr[1], pa0); pa1 = MF(kf[3], qr[1], pa1);
;     SBAR(); ATT_KLD(0, 1); SBAR();
;     pa0 = MF(kf[0], qr[2], pa0); pa1 = MF(kf[1], qr[2], pa1); pa0 = MF(kf[2], qr[3], pa0); pa1 = MF(kf[3], qr[3], pa1);
;     if (KIND == 2) { pa0 = MF(x0, ones, pa0); pa1 = MF(x1, ones, pa1); }
;     ATT_FIX(pa0, pa1, ATT_TILE(0));
;     { float rm = max3f(pa0[0], pa0[1], pa1[0]), rm2 = max3f(pa0[2], pa0[3], pa1[1]); rm = max3f(rm, pa1[2], pa1[3]);
; #pragma unroll
;       for (int r = 4; r < 16; r += 4) { rm = max3f(rm, pa0[r], pa0[r + 1]); rm2 = max3f(rm2, pa0[r + 2], pa0[r + 3]); rm = max3f(rm, pa1[r], pa1[r + 1]); rm2 = max3f(rm2, pa1[r + 2], pa1[r + 3]); }
;       rm = swapmax(max3f(rm, rm2, rm2)); ATT_DECIDE(pa0, pa1, rm); }
.LBB0_374:
	s_ashr_i32 s6, s6, 7
	s_add_i32 s6, s6, s33
	s_max_i32 s7, s6, 8
	s_add_i32 s7, s7, -8
	s_cmp_lt_i32 s20, s7
	s_cselect_b64 s[10:11], -1, 0
	s_cmp_gt_i32 s20, s6
	s_cselect_b64 s[12:13], -1, 0
	s_or_b64 vcc, s[10:11], s[12:13]
	s_nop 1
	v_cndmask_b32_e32 v52, v20, v245, vcc
	v_cndmask_b32_e32 v101, v5, v245, vcc
	v_cndmask_b32_e32 v100, v4, v245, vcc
	v_max3_f32 v0, v100, v101, v52
	v_cndmask_b32_e32 v55, v23, v245, vcc
	v_cndmask_b32_e32 v54, v22, v245, vcc
	v_cndmask_b32_e32 v53, v21, v245, vcc
	v_cndmask_b32_e32 v103, v7, v245, vcc
	v_cndmask_b32_e32 v102, v6, v245, vcc
	v_max3_f32 v1, v102, v103, v53
	v_max3_f32 v0, v0, v54, v55
	v_cndmask_b32_e32 v107, v11, v245, vcc
	v_cndmask_b32_e32 v106, v10, v245, vcc
	v_cndmask_b32_e32 v105, v9, v245, vcc
	v_cndmask_b32_e32 v104, v8, v245, vcc
	v_max3_f32 v0, v0, v104, v105
	v_max3_f32 v1, v1, v106, v107
	v_cndmask_b32_e32 v59, v27, v245, vcc
	v_cndmask_b32_e32 v58, v26, v245, vcc
	v_cndmask_b32_e32 v57, v25, v245, vcc
	v_cndmask_b32_e32 v56, v24, v245, vcc
	v_max3_f32 v0, v0, v56, v57
	v_max3_f32 v1, v1, v58, v59
	v_cndmask_b32_e32 v111, v15, v245, vcc
	v_cndmask_b32_e32 v110, v14, v245, vcc
	v_cndmask_b32_e32 v109, v13, v245, vcc
	v_cndmask_b32_e32 v108, v12, v245, vcc
	v_max3_f32 v0, v0, v108, v109
	v_max3_f32 v1, v1, v110, v111
	v_cndmask_b32_e32 v63, v31, v245, vcc
	v_cndmask_b32_e32 v62, v30, v245, vcc
	v_cndmask_b32_e32 v61, v29, v245, vcc
	v_cndmask_b32_e32 v60, v28, v245, vcc
	v_max3_f32 v0, v0, v60, v61
	v_max3_f32 v1, v1, v62, v63
	v_cndmask_b32_e32 v115, v19, v245, vcc
	v_cndmask_b32_e32 v114, v18, v245, vcc
	v_cndmask_b32_e32 v113, v17, v245, vcc
	v_cndmask_b32_e32 v112, v16, v245, vcc
	v_max3_f32 v0, v0, v112, v113
	v_max3_f32 v1, v1, v114, v115
	v_cndmask_b32_e32 v67, v35, v245, vcc
	v_cndmask_b32_e32 v66, v34, v245, vcc
	v_cndmask_b32_e32 v65, v33, v245, vcc
	v_cndmask_b32_e32 v64, v32, v245, vcc
	v_max3_f32 v0, v0, v64, v65
	v_max3_f32 v1, v1, v66, v67
	s_nop 0
	v_max3_f32 v0, v0, v1, v1
	s_nop 0
	v_mov_b32_e32 v1, v0
	s_nop 1
	v_permlane32_swap_b32_e32 v0, v1


	v_max_f32_e32 v0, v0, v1
	v_cmp_lt_f32_e32 vcc, s88, v0
	s_cbranch_vccz .LBB0_416
	v_max_f32_e32 v0, v0, v0
	v_max_f32_e32 v0, 0, v0
	v_exp_f32_e64 v1, -v0
	v_sub_f32_e32 v36, v36, v0
	v_sub_f32_e32 v115, v115, v0
	v_sub_f32_e32 v114, v114, v0
	v_mul_f32_e32 v4, 0, v1
	v_mov_b32_e32 v5, v4
	v_mov_b32_e32 v6, v4
	v_mov_b32_e32 v7, v4
	v_mov_b32_e32 v8, v4
	v_mov_b32_e32 v9, v4
	v_mov_b32_e32 v10, v4
	v_mov_b32_e32 v11, v4
	v_mov_b32_e32 v12, v4
	v_mov_b32_e32 v13, v4
	v_mov_b32_e32 v14, v4
	v_mov_b32_e32 v15, v4
	v_mov_b32_e32 v16, v4
	v_mov_b32_e32 v17, v4
	v_mov_b32_e32 v18, v4
	v_mov_b32_e32 v19, v4
	v_mov_b32_e32 v20, v4
	v_mov_b32_e32 v21, v4
	v_mov_b32_e32 v22, v4
	v_mov_b32_e32 v23, v4
	v_mov_b32_e32 v24, v4
	v_mov_b32_e32 v25, v4
	v_mov_b32_e32 v26, v4
	v_mov_b32_e32 v27, v4
	v_mov_b32_e32 v28, v4
	v_mov_b32_e32 v29, v4
	v_mov_b32_e32 v30, v4
	v_mov_b32_e32 v31, v4
	v_mov_b32_e32 v32, v4
	v_mov_b32_e32 v33, v4
	v_mov_b32_e32 v34, v4
	v_mov_b32_e32 v35, v4
	v_sub_f32_e32 v113, v113, v0
	v_sub_f32_e32 v112, v112, v0
	v_sub_f32_e32 v111, v111, v0
	v_sub_f32_e32 v110, v110, v0
	v_sub_f32_e32 v109, v109, v0
	v_sub_f32_e32 v108, v108, v0
	v_sub_f32_e32 v107, v107, v0
	v_sub_f32_e32 v106, v106, v0
	v_sub_f32_e32 v105, v105, v0
	v_sub_f32_e32 v104, v104, v0
	v_sub_f32_e32 v103, v103, v0
	v_sub_f32_e32 v102, v102, v0
	v_sub_f32_e32 v101, v101, v0
	v_sub_f32_e32 v100, v100, v0
	v_sub_f32_e32 v67, v67, v0
	v_sub_f32_e32 v66, v66, v0
	v_sub_f32_e32 v65, v65, v0
	v_sub_f32_e32 v64, v64, v0
	v_sub_f32_e32 v63, v63, v0
	v_sub_f32_e32 v62, v62, v0
	v_sub_f32_e32 v61, v61, v0
	v_sub_f32_e32 v60, v60, v0
	v_sub_f32_e32 v59, v59, v0
	v_sub_f32_e32 v58, v58, v0
	v_sub_f32_e32 v57, v57, v0
	v_sub_f32_e32 v56, v56, v0
	v_sub_f32_e32 v55, v55, v0
	v_sub_f32_e32 v54, v54, v0
	v_sub_f32_e32 v53, v53, v0
	v_sub_f32_e32 v52, v52, v0
	v_mov_b32_e32 v37, v36
	v_mov_b32_e32 v38, v36
	v_mov_b32_e32 v39, v36
	v_mov_b32_e32 v40, v36
	v_mov_b32_e32 v41, v36
	v_mov_b32_e32 v42, v36
	v_mov_b32_e32 v43, v36
	v_mov_b32_e32 v44, v36
	v_mov_b32_e32 v45, v36
	v_mov_b32_e32 v46, v36
	v_mov_b32_e32 v47, v36
	v_mov_b32_e32 v48, v36
	v_mov_b32_e32 v49, v36
	v_mov_b32_e32 v50, v36
	v_mov_b32_e32 v51, v36
	v_mov_b32_e32 v159, v4
	s_cmp_lt_i32 s4, 0
	s_cbranch_scc0 .LBB0_417
	s_branch .LBB0_437

; DI float max3f(float a, float b, float c) { float r; asm("v_max3_f32 %0, %1, %2, %3" : "=v"(r) : "v"(a), "v"(b), "v"(c)); return r; }
; DI float swapmax(float m) { auto rr = __builtin_amdgcn_permlane32_swap(__float_as_uint(m), __float_as_uint(m), false, false); return fmaxf(__uint_as_float(rr[0]), __uint_as_float(rr[1])); }
; #define ATT_DECIDE(P0, P1, rm_) do { if (__any((rm_) > 6.0f)) { const float dl = fmaxf((rm_), 0.f); mhat += dl; const float f = EX(-dl); lsum *= f; \
;             _Pragma("unroll") for (int r = 0; r < 16; ++r) { P0[r] -= dl; P1[r] -= dl; negm[r] -= dl; } \
;             _Pragma("unroll") for (int i2 = 0; i2 < NDB; ++i2) _Pragma("unroll") for (int r = 0; r < 16; ++r) o[i2][r] *= f; } } while (0)
; template <int KIND> DI void attn_unit(const Params& P, int b, int h, int qb, char* shm, float lam, bool dry = false) {
;     ...
;     { float rm = max3f(pa0[0], pa0[1], pa1[0]), rm2 = max3f(pa0[2], pa0[3], pa1[1]); rm = max3f(rm, pa1[2], pa1[3]);
; #pragma unroll
;       for (int r = 4; r < 16; r += 4) { rm = max3f(rm, pa0[r], pa0[r + 1]); rm2 = max3f(rm2, pa0[r + 2], pa0[r + 3]); rm = max3f(rm, pa1[r], pa1[r + 1]); rm2 = max3f(rm2, pa1[r + 2], pa1[r + 3]); }
;       rm = swapmax(max3f(rm, rm2, rm2)); ATT_DECIDE(pa0, pa1, rm); }
.LBB0_390:
	s_nop 0
	v_max3_f32 v37, v20, v21, v84
	v_max3_f32 v42, v22, v23, v85
	s_nop 0
	v_max3_f32 v37, v37, v86, v87
	v_max3_f32 v42, v42, v26, v27
	s_nop 0
	v_max3_f32 v37, v37, v24, v25
	v_max3_f32 v42, v42, v90, v91
	s_nop 0
	v_max3_f32 v37, v37, v88, v89
	v_max3_f32 v42, v42, v30, v31
	s_nop 0
	v_max3_f32 v37, v37, v28, v29
	v_max3_f32 v42, v42, v94, v95
	s_nop 0
	v_max3_f32 v37, v37, v92, v93
	v_max3_f32 v42, v42, v34, v35
	s_nop 0
	v_max3_f32 v37, v37, v32, v33
	v_max3_f32 v42, v42, v98, v99
	s_nop 0
	v_max3_f32 v37, v37, v96, v97
	s_nop 0
	v_max3_f32 v37, v37, v42, v42
	s_nop 0
	v_mov_b32_e32 v42, v37
	s_nop 1
	v_permlane32_swap_b32_e32 v37, v42


	v_max_f32_e32 v37, v37, v42
	v_cmp_lt_f32_e32 vcc, s88, v37
	s_cbranch_vccz .LBB0_392
	v_max_f32_e32 v5, v37, v37
	v_max_f32_e32 v5, 0, v5
	v_exp_f32_e64 v6, -v5
	v_sub_f32_e32 v4, v4, v5
	v_sub_f32_e32 v35, v35, v5
	v_sub_f32_e32 v34, v34, v5
	v_mul_f32_e32 v100, 0, v6
	v_sub_f32_e32 v33, v33, v5
	v_sub_f32_e32 v32, v32, v5
	v_sub_f32_e32 v31, v31, v5
	v_sub_f32_e32 v30, v30, v5
	v_sub_f32_e32 v29, v29, v5
	v_sub_f32_e32 v28, v28, v5
	v_sub_f32_e32 v27, v27, v5
	v_sub_f32_e32 v26, v26, v5
	v_sub_f32_e32 v25, v25, v5
	v_sub_f32_e32 v24, v24, v5
	v_sub_f32_e32 v23, v23, v5
	v_sub_f32_e32 v22, v22, v5
	v_sub_f32_e32 v21, v21, v5
	v_sub_f32_e32 v20, v20, v5
	v_sub_f32_e32 v99, v99, v5
	v_sub_f32_e32 v98, v98, v5
	v_sub_f32_e32 v97, v97, v5
	v_sub_f32_e32 v96, v96, v5
	v_sub_f32_e32 v95, v95, v5
	v_sub_f32_e32 v94, v94, v5
	v_sub_f32_e32 v93, v93, v5
	v_sub_f32_e32 v92, v92, v5
	v_sub_f32_e32 v91, v91, v5
	v_sub_f32_e32 v90, v90, v5
	v_sub_f32_e32 v89, v89, v5
	v_sub_f32_e32 v88, v88, v5
	v_sub_f32_e32 v87, v87, v5
	v_sub_f32_e32 v86, v86, v5
	v_sub_f32_e32 v85, v85, v5
	v_sub_f32_e32 v84, v84, v5
	v_mov_b32_e32 v5, v4
	v_mov_b32_e32 v6, v4
	v_mov_b32_e32 v7, v4
	v_mov_b32_e32 v8, v4
	v_mov_b32_e32 v9, v4
	v_mov_b32_e32 v10, v4
	v_mov_b32_e32 v11, v4
	v_mov_b32_e32 v12, v4
	v_mov_b32_e32 v13, v4
	v_mov_b32_e32 v14, v4
	v_mov_b32_e32 v15, v4
	v_mov_b32_e32 v16, v4
	v_mov_b32_e32 v17, v4
	v_mov_b32_e32 v18, v4
	v_mov_b32_e32 v19, v4
	s_branch .LBB0_393

; DI float max3f(float a, float b, float c) { float r; asm("v_max3_f32 %0, %1, %2, %3" : "=v"(r) : "v"(a), "v"(b), "v"(c)); return r; }
; DI float swapmax(float m) { auto rr = __builtin_amdgcn_permlane32_swap(__float_as_uint(m), __float_as_uint(m), false, false); return fmaxf(__uint_as_float(rr[0]), __uint_as_float(rr[1])); }
; #define SBAR() __builtin_amdgcn_sched_barrier(0)
; #define PIN(x) asm volatile("" : "+v"(x))
; template <int KIND> DI void attn_unit(const Params& P, int b, int h, int qb, char* shm, float lam, bool dry = false) {
;     ...
;         ATT_FIX(pb0, pb1, ATT_TILE(i + 1));
;         float rm, rm2;
;         if (NDB == 4) {
;             LDV(11); PVM(8); rm = max3f(pb0[0], pb0[1], pb1[0]); rm2 = max3f(pb0[2], pb0[3], pb1[1]); PIN(rm); PIN(rm2); SBAR();
;             LDV(12); PVM(9); rm = max3f(rm, pb1[2], pb1[3]); rm2 = max3f(rm2, pb0[4], pb0[5]); PIN(rm); PIN(rm2); SBAR();
;             LDV(13); PVM(10); rm = max3f(rm, pb0[6], pb0[7]); rm2 = max3f(rm2, pb1[4], pb1[5]); PIN(rm); PIN(rm2); SBAR();
;             LDV(14); PVM(11); rm = max3f(rm, pb1[6], pb1[7]); rm2 = max3f(rm2, pb0[8], pb0[9]); PIN(rm); PIN(rm2); SBAR();
;             LDV(15); PVM(12); rm = max3f(rm, pb0[10], pb0[11]); rm2 = max3f(rm2, pb1[8], pb1[9]); PIN(rm); PIN(rm2); SBAR();
;             PVM(13); rm = max3f(rm, pb1[10], pb1[11]); rm2 = max3f(rm2, pb0[12], pb0[13]); PIN(rm); PIN(rm2); SBAR();
;             PVM(14); rm = max3f(rm, pb0[14], pb0[15]); rm2 = max3f(rm2, pb1[12], pb1[13]); PIN(rm); PIN(rm2); SBAR();
;             PVM(15); rm = max3f(rm, pb1[14], pb1[15]); PIN(rm); SBAR();
;         } else {
;             LDV(7); PVM(4); rm = max3f(pb0[0], pb0[1], pb1[0]); rm2 = max3f(pb0[2], pb0[3], pb1[1]); rm = max3f(rm, pb1[2], pb1[3]); rm2 = max3f(rm2, pb0[4], pb0[5]); PIN(rm); PIN(rm2); SBAR();
;             PVM(5); rm = max3f(rm, pb0[6], pb0[7]); rm2 = max3f(rm2, pb1[4], pb1[5]); rm = max3f(rm, pb1[6], pb1[7]); rm2 = max3f(rm2, pb0[8], pb0[9]); PIN(rm); PIN(rm2); SBAR();
;             PVM(6); rm = max3f(rm, pb0[10], pb0[11]); rm2 = max3f(rm2, pb1[8], pb1[9]); rm = max3f(rm, pb1[10], pb1[11]); rm2 = max3f(rm2, pb0[12], pb0[13]); PIN(rm); PIN(rm2); SBAR();
;             PVM(7); rm = max3f(rm, pb0[14], pb0[15]); rm2 = max3f(rm2, pb1[12], pb1[13]); rm = max3f(rm, pb1[14], pb1[15]); PIN(rm); PIN(rm2); SBAR();
;         }
;     ...
;         rm = swapmax(max3f(rm, rm2, rm2));
.LBB0_397:
	s_lshl_b32 s6, s3, 1
	s_lshr_b32 s7, s9, 1
	s_or_b32 s7, s7, s6
	s_waitcnt lgkmcnt(4)
	v_mfma_f32_32x32x16_bf16 v[68:83], v[172:175], v[164:167], v[68:83]
	s_cmp_eq_u32 s7, 0
	s_cselect_b64 vcc, -1, 0
	v_add_f32_e32 v197, v100, v101
	v_cndmask_b32_e32 v103, v119, v245, vcc
	v_cndmask_b32_e32 v102, v118, v245, vcc
	v_cndmask_b32_e32 v101, v117, v245, vcc
	v_cndmask_b32_e32 v100, v116, v245, vcc
	ds_read_b64_tr_b16 v[116:117], v196 offset:30720
	ds_read_b64_tr_b16 v[118:119], v196 offset:31232
	v_cndmask_b32_e32 v99, v147, v245, vcc
	v_cndmask_b32_e32 v98, v146, v245, vcc
	v_cndmask_b32_e32 v97, v145, v245, vcc
	v_cndmask_b32_e32 v96, v144, v245, vcc
	v_cndmask_b32_e32 v95, v143, v245, vcc
	v_cndmask_b32_e32 v94, v142, v245, vcc
	v_cndmask_b32_e32 v93, v141, v245, vcc
	v_cndmask_b32_e32 v92, v140, v245, vcc
	v_cndmask_b32_e32 v91, v139, v245, vcc
	v_cndmask_b32_e32 v90, v138, v245, vcc
	v_cndmask_b32_e32 v89, v137, v245, vcc
	v_cndmask_b32_e32 v88, v136, v245, vcc
	v_cndmask_b32_e32 v87, v135, v245, vcc
	v_cndmask_b32_e32 v86, v134, v245, vcc
	v_cndmask_b32_e32 v85, v133, v245, vcc
	v_cndmask_b32_e32 v84, v132, v245, vcc
	v_cndmask_b32_e32 v115, v131, v245, vcc
	v_cndmask_b32_e32 v114, v130, v245, vcc
	v_cndmask_b32_e32 v113, v129, v245, vcc
	v_cndmask_b32_e32 v112, v128, v245, vcc
	v_cndmask_b32_e32 v111, v127, v245, vcc
	v_cndmask_b32_e32 v110, v126, v245, vcc
	v_cndmask_b32_e32 v109, v125, v245, vcc
	v_cndmask_b32_e32 v108, v124, v245, vcc
	v_cndmask_b32_e32 v107, v123, v245, vcc
	v_cndmask_b32_e32 v106, v122, v245, vcc
	v_cndmask_b32_e32 v105, v121, v245, vcc
	v_cndmask_b32_e32 v104, v120, v245, vcc
	v_max3_f32 v124, v100, v101, v84
	v_max3_f32 v125, v102, v103, v85
	s_nop 0
	s_waitcnt lgkmcnt(4)
	v_mfma_f32_32x32x16_bf16 v[52:67], v[176:179], v[164:167], v[52:67]
	ds_read_b64_tr_b16 v[120:121], v196 offset:19456
	ds_read_b64_tr_b16 v[122:123], v196 offset:19968
	v_max3_f32 v128, v124, v86, v87
	v_max3_f32 v129, v125, v104, v105
	s_nop 0
	s_waitcnt lgkmcnt(4)
	v_mfma_f32_32x32x16_bf16 v[36:51], v[180:183], v[164:167], v[36:51]
	ds_read_b64_tr_b16 v[124:125], v196 offset:23552
	ds_read_b64_tr_b16 v[126:127], v196 offset:24064
	v_max3_f32 v132, v128, v106, v107
	v_max3_f32 v133, v129, v88, v89
	s_nop 0
	s_waitcnt lgkmcnt(4)
	v_mfma_f32_32x32x16_bf16 v[20:35], v[116:119], v[164:167], v[20:35]
	ds_read_b64_tr_b16 v[128:129], v196 offset:27648
	ds_read_b64_tr_b16 v[130:131], v196 offset:28160
	v_max3_f32 v132, v132, v90, v91
	v_max3_f32 v133, v133, v108, v109
	s_nop 0
	s_waitcnt lgkmcnt(4)
	v_mfma_f32_32x32x16_bf16 v[68:83], v[120:123], v[168:171], v[68:83]
	ds_read_b64_tr_b16 v[116:117], v196 offset:31744
	ds_read_b64_tr_b16 v[118:119], v196 offset:32256
	v_max3_f32 v120, v132, v110, v111
	v_max3_f32 v121, v133, v92, v93
	s_nop 0
	s_waitcnt lgkmcnt(4)
	v_mfma_f32_32x32x16_bf16 v[52:67], v[124:127], v[168:171], v[52:67]
	v_max3_f32 v120, v120, v94, v95
	v_max3_f32 v121, v121, v112, v113
	s_nop 0
	s_waitcnt lgkmcnt(2)
	v_mfma_f32_32x32x16_bf16 v[36:51], v[128:131], v[168:171], v[36:51]
	v_max3_f32 v120, v120, v114, v115
	v_max3_f32 v121, v121, v96, v97
	s_nop 0
	s_waitcnt lgkmcnt(0)
	v_mfma_f32_32x32x16_bf16 v[20:35], v[116:119], v[168:171], v[20:35]
	v_max3_f32 v116, v120, v98, v99
	s_nop 0
	s_nop 0
	v_max3_f32 v116, v116, v121, v121
	s_nop 0
	v_mov_b32_e32 v117, v116
	s_nop 1
	v_permlane32_swap_b32_e32 v116, v117


	v_max_f32_e32 v116, v116, v117
	v_cmp_lt_f32_e32 vcc, s88, v116
	s_cbranch_vccz .LBB0_399
	v_max_f32_e32 v116, v116, v116
	v_max_f32_e32 v117, 0, v116
	v_exp_f32_e64 v116, -v117
	v_sub_f32_e32 v115, v115, v117
	v_sub_f32_e32 v114, v114, v117
	v_sub_f32_e32 v113, v113, v117
	v_pk_mul_f32 v[82:83], v[82:83], v[116:117] op_sel_hi:[1,0]
	v_pk_mul_f32 v[80:81], v[80:81], v[116:117] op_sel_hi:[1,0]
	v_pk_mul_f32 v[78:79], v[78:79], v[116:117] op_sel_hi:[1,0]
	v_pk_mul_f32 v[76:77], v[76:77], v[116:117] op_sel_hi:[1,0]
	v_pk_mul_f32 v[74:75], v[74:75], v[116:117] op_sel_hi:[1,0]
	v_pk_mul_f32 v[72:73], v[72:73], v[116:117] op_sel_hi:[1,0]
	v_pk_mul_f32 v[70:71], v[70:71], v[116:117] op_sel_hi:[1,0]
	v_pk_mul_f32 v[68:69], v[68:69], v[116:117] op_sel_hi:[1,0]
	v_pk_mul_f32 v[66:67], v[66:67], v[116:117] op_sel_hi:[1,0]
	v_pk_mul_f32 v[64:65], v[64:65], v[116:117] op_sel_hi:[1,0]
	v_pk_mul_f32 v[62:63], v[62:63], v[116:117] op_sel_hi:[1,0]
	v_pk_mul_f32 v[60:61], v[60:61], v[116:117] op_sel_hi:[1,0]
	v_pk_mul_f32 v[58:59], v[58:59], v[116:117] op_sel_hi:[1,0]
	v_pk_mul_f32 v[56:57], v[56:57], v[116:117] op_sel_hi:[1,0]
	v_pk_mul_f32 v[54:55], v[54:55], v[116:117] op_sel_hi:[1,0]
	v_pk_mul_f32 v[52:53], v[52:53], v[116:117] op_sel_hi:[1,0]
	v_pk_mul_f32 v[50:51], v[50:51], v[116:117] op_sel_hi:[1,0]
	v_pk_mul_f32 v[48:49], v[48:49], v[116:117] op_sel_hi:[1,0]
	v_pk_mul_f32 v[46:47], v[46:47], v[116:117] op_sel_hi:[1,0]
	v_pk_mul_f32 v[44:45], v[44:45], v[116:117] op_sel_hi:[1,0]
	v_pk_mul_f32 v[42:43], v[42:43], v[116:117] op_sel_hi:[1,0]
	v_pk_mul_f32 v[40:41], v[40:41], v[116:117] op_sel_hi:[1,0]
	v_pk_mul_f32 v[38:39], v[38:39], v[116:117] op_sel_hi:[1,0]
	v_pk_mul_f32 v[36:37], v[36:37], v[116:117] op_sel_hi:[1,0]
	v_pk_mul_f32 v[34:35], v[34:35], v[116:117] op_sel_hi:[1,0]
	v_pk_mul_f32 v[32:33], v[32:33], v[116:117] op_sel_hi:[1,0]
	v_pk_mul_f32 v[30:31], v[30:31], v[116:117] op_sel_hi:[1,0]
	v_pk_mul_f32 v[28:29], v[28:29], v[116:117] op_sel_hi:[1,0]
	v_pk_mul_f32 v[26:27], v[26:27], v[116:117] op_sel_hi:[1,0]
	v_pk_mul_f32 v[24:25], v[24:25], v[116:117] op_sel_hi:[1,0]
	v_pk_mul_f32 v[22:23], v[22:23], v[116:117] op_sel_hi:[1,0]
	v_pk_mul_f32 v[20:21], v[20:21], v[116:117] op_sel_hi:[1,0]
	v_sub_f32_e32 v112, v112, v117
	v_sub_f32_e32 v111, v111, v117
	v_sub_f32_e32 v110, v110, v117
	v_sub_f32_e32 v109, v109, v117
	v_sub_f32_e32 v108, v108, v117
	v_sub_f32_e32 v107, v107, v117
	v_sub_f32_e32 v106, v106, v117
	v_sub_f32_e32 v105, v105, v117
	v_sub_f32_e32 v104, v104, v117
	v_sub_f32_e32 v103, v103, v117
	v_sub_f32_e32 v102, v102, v117
	v_sub_f32_e32 v101, v101, v117
	v_sub_f32_e32 v100, v100, v117
	v_sub_f32_e32 v99, v99, v117
	v_sub_f32_e32 v98, v98, v117
	v_sub_f32_e32 v97, v97, v117
	v_sub_f32_e32 v96, v96, v117
	v_sub_f32_e32 v95, v95, v117
	v_sub_f32_e32 v94, v94, v117
	v_sub_f32_e32 v93, v93, v117
	v_sub_f32_e32 v92, v92, v117
	v_sub_f32_e32 v91, v91, v117
	v_sub_f32_e32 v90, v90, v117
	v_sub_f32_e32 v89, v89, v117
	v_sub_f32_e32 v88, v88, v117
	v_sub_f32_e32 v87, v87, v117
	v_sub_f32_e32 v86, v86, v117
	v_sub_f32_e32 v85, v85, v117
	v_sub_f32_e32 v84, v84, v117
	v_sub_f32_e32 v19, v19, v117
	v_sub_f32_e32 v18, v18, v117
	v_sub_f32_e32 v17, v17, v117
	v_sub_f32_e32 v16, v16, v117
	v_sub_f32_e32 v15, v15, v117
	v_sub_f32_e32 v14, v14, v117
	v_sub_f32_e32 v13, v13, v117
	v_sub_f32_e32 v12, v12, v117
	v_sub_f32_e32 v11, v11, v117
	v_sub_f32_e32 v10, v10, v117
	v_sub_f32_e32 v9, v9, v117
	v_sub_f32_e32 v8, v8, v117
	v_sub_f32_e32 v7, v7, v117
	v_sub_f32_e32 v6, v6, v117
	v_sub_f32_e32 v5, v5, v117
	v_sub_f32_e32 v4, v4, v117
	v_mul_f32_e32 v197, v197, v116

; DI float max3f(float a, float b, float c) { float r; asm("v_max3_f32 %0, %1, %2, %3" : "=v"(r) : "v"(a), "v"(b), "v"(c)); return r; }
; DI float swapmax(float m) { auto rr = __builtin_amdgcn_permlane32_swap(__float_as_uint(m), __float_as_uint(m), false, false); return fmaxf(__uint_as_float(rr[0]), __uint_as_float(rr[1])); }
; #define SBAR() __builtin_amdgcn_sched_barrier(0)
; #define PIN(x) asm volatile("" : "+v"(x))
; #define LDV(j_) do { if ((j_) < 4 * NDB) { const lds_cptr a_ = vp + ((j_) % NDB) * 4096 + ((j_) / NDB) * 1024; const s16x4 lo_ = vtr(a_), hi_ = vtr(a_ + 512); \
;             vq[(j_) & 3] = (bf16x8){lo_[0], lo_[1], lo_[2], lo_[3], hi_[0], hi_[1], hi_[2], hi_[3]}; } } while (0)
; #define PVM(j_) o[(j_) % NDB] = MF(vq[(j_) & 3], pw[(j_) / NDB], o[(j_) % NDB])
; template <int KIND> DI void attn_unit(const Params& P, int b, int h, int qb, char* shm, float lam, bool dry = false) {
;     ...
;             PVM(13); rm = max3f(rm, pb1[10], pb1[11]); rm2 = max3f(rm2, pb0[12], pb0[13]); PIN(rm); PIN(rm2); SBAR();
;             PVM(14); rm = max3f(rm, pb0[14], pb0[15]); rm2 = max3f(rm2, pb1[12], pb1[13]); PIN(rm); PIN(rm2); SBAR();
;             PVM(15); rm = max3f(rm, pb1[14], pb1[15]); PIN(rm); SBAR();
;         } else {
;             LDV(7); PVM(4); rm = max3f(pb0[0], pb0[1], pb1[0]); rm2 = max3f(pb0[2], pb0[3], pb1[1]); rm = max3f(rm, pb1[2], pb1[3]); rm2 = max3f(rm2, pb0[4], pb0[5]); PIN(rm); PIN(rm2); SBAR();
;             PVM(5); rm = max3f(rm, pb0[6], pb0[7]); rm2 = max3f(rm2, pb1[4], pb1[5]); rm = max3f(rm, pb1[6], pb1[7]); rm2 = max3f(rm2, pb0[8], pb0[9]); PIN(rm); PIN(rm2); SBAR();
;             PVM(6); rm = max3f(rm, pb0[10], pb0[11]); rm2 = max3f(rm2, pb1[8], pb1[9]); rm = max3f(rm, pb1[10], pb1[11]); rm2 = max3f(rm2, pb0[12], pb0[13]); PIN(rm); PIN(rm2); SBAR();
;             PVM(7); rm = max3f(rm, pb0[14], pb0[15]); rm2 = max3f(rm2, pb1[12], pb1[13]); rm = max3f(rm, pb1[14], pb1[15]); PIN(rm); PIN(rm2); SBAR();
;         }
;     ...
;         rm = swapmax(max3f(rm, rm2, rm2));
.Lat1_nd3:
	ds_read_b64_tr_b16 v[84:85], v190 offset:31744
	ds_read_b64_tr_b16 v[86:87], v190 offset:32256
	v_max3_f32 v100, v100, v126, v127
	v_max3_f32 v101, v101, v140, v141
	s_waitcnt lgkmcnt(4)
	v_mfma_f32_32x32x16_bf16 v[52:67], v[92:95], v[112:115], v[52:67]
	v_max3_f32 v100, v100, v142, v143
	v_max3_f32 v101, v101, v128, v129
	s_waitcnt lgkmcnt(2)
	v_mfma_f32_32x32x16_bf16 v[36:51], v[96:99], v[112:115], v[36:51]
	v_max3_f32 v100, v100, v130, v131
	v_max3_f32 v101, v101, v144, v145
	v_max3_f32 v100, v100, v146, v147
	v_max3_f32 v100, v100, v101, v101
	v_mov_b32_e32 v101, v100
	s_waitcnt lgkmcnt(0)
	v_mfma_f32_32x32x16_bf16 v[20:35], v[84:87], v[112:115], v[20:35]
	s_add_i32 s3, s3, 1
	s_cmp_ge_u32 s3, s18
	v_permlane32_swap_b32_e32 v100, v101
	s_cbranch_scc1 .LBB0_408


; #define ATT_DECIDE(P0, P1, rm_) do { if (__any((rm_) > 6.0f)) { const float dl = fmaxf((rm_), 0.f); mhat += dl; const float f = EX(-dl); lsum *= f; \
;             _Pragma("unroll") for (int r = 0; r < 16; ++r) { P0[r] -= dl; P1[r] -= dl; negm[r] -= dl; } \
;             _Pragma("unroll") for (int i2 = 0; i2 < NDB; ++i2) _Pragma("unroll") for (int r = 0; r < 16; ++r) o[i2][r] *= f; } } while (0)
; template <int KIND> DI void attn_unit(const Params& P, int b, int h, int qb, char* shm, float lam, bool dry = false) {
;     ...
;         if (i + 1 < nt_eff) ATT_DECIDE(pb0, pb1, rm);
	v_max_f32_e32 v100, v100, v101
	v_cmp_lt_f32_e32 vcc, s88, v100
	s_cbranch_vccz .LBB0_408
	v_max_f32_e32 v100, v100, v100
	v_max_f32_e32 v101, 0, v100
	v_exp_f32_e64 v100, -v101
	v_sub_f32_e32 v131, v131, v101
	v_sub_f32_e32 v130, v130, v101
	v_sub_f32_e32 v129, v129, v101
	v_pk_mul_f32 v[82:83], v[82:83], v[100:101] op_sel_hi:[1,0]
	v_pk_mul_f32 v[80:81], v[80:81], v[100:101] op_sel_hi:[1,0]
	v_pk_mul_f32 v[78:79], v[78:79], v[100:101] op_sel_hi:[1,0]
	v_pk_mul_f32 v[76:77], v[76:77], v[100:101] op_sel_hi:[1,0]
	v_pk_mul_f32 v[74:75], v[74:75], v[100:101] op_sel_hi:[1,0]
	v_pk_mul_f32 v[72:73], v[72:73], v[100:101] op_sel_hi:[1,0]
	v_pk_mul_f32 v[70:71], v[70:71], v[100:101] op_sel_hi:[1,0]
	v_pk_mul_f32 v[68:69], v[68:69], v[100:101] op_sel_hi:[1,0]
	v_pk_mul_f32 v[66:67], v[66:67], v[100:101] op_sel_hi:[1,0]
	v_pk_mul_f32 v[64:65], v[64:65], v[100:101] op_sel_hi:[1,0]
	v_pk_mul_f32 v[62:63], v[62:63], v[100:101] op_sel_hi:[1,0]
	v_pk_mul_f32 v[60:61], v[60:61], v[100:101] op_sel_hi:[1,0]
	v_pk_mul_f32 v[58:59], v[58:59], v[100:101] op_sel_hi:[1,0]
	v_pk_mul_f32 v[56:57], v[56:57], v[100:101] op_sel_hi:[1,0]
	v_pk_mul_f32 v[54:55], v[54:55], v[100:101] op_sel_hi:[1,0]
	v_pk_mul_f32 v[52:53], v[52:53], v[100:101] op_sel_hi:[1,0]
	v_pk_mul_f32 v[50:51], v[50:51], v[100:101] op_sel_hi:[1,0]
	v_pk_mul_f32 v[48:49], v[48:49], v[100:101] op_sel_hi:[1,0]
	v_pk_mul_f32 v[46:47], v[46:47], v[100:101] op_sel_hi:[1,0]
	v_pk_mul_f32 v[44:45], v[44:45], v[100:101] op_sel_hi:[1,0]
	v_pk_mul_f32 v[42:43], v[42:43], v[100:101] op_sel_hi:[1,0]
	v_pk_mul_f32 v[40:41], v[40:41], v[100:101] op_sel_hi:[1,0]
	v_pk_mul_f32 v[38:39], v[38:39], v[100:101] op_sel_hi:[1,0]
	v_pk_mul_f32 v[36:37], v[36:37], v[100:101] op_sel_hi:[1,0]
	v_pk_mul_f32 v[34:35], v[34:35], v[100:101] op_sel_hi:[1,0]
	v_pk_mul_f32 v[32:33], v[32:33], v[100:101] op_sel_hi:[1,0]
	v_pk_mul_f32 v[30:31], v[30:31], v[100:101] op_sel_hi:[1,0]
	v_pk_mul_f32 v[28:29], v[28:29], v[100:101] op_sel_hi:[1,0]
	v_pk_mul_f32 v[26:27], v[26:27], v[100:101] op_sel_hi:[1,0]
	v_pk_mul_f32 v[24:25], v[24:25], v[100:101] op_sel_hi:[1,0]
	v_pk_mul_f32 v[22:23], v[22:23], v[100:101] op_sel_hi:[1,0]
	v_pk_mul_f32 v[20:21], v[20:21], v[100:101] op_sel_hi:[1,0]
	v_sub_f32_e32 v128, v128, v101
	v_sub_f32_e32 v127, v127, v101
	v_sub_f32_e32 v126, v126, v101
	v_sub_f32_e32 v125, v125, v101
	v_sub_f32_e32 v124, v124, v101
	v_sub_f32_e32 v123, v123, v101
	v_sub_f32_e32 v122, v122, v101
	v_sub_f32_e32 v121, v121, v101
	v_sub_f32_e32 v120, v120, v101
	v_sub_f32_e32 v119, v119, v101
	v_sub_f32_e32 v118, v118, v101
	v_sub_f32_e32 v117, v117, v101
	v_sub_f32_e32 v116, v116, v101
	v_sub_f32_e32 v147, v147, v101
	v_sub_f32_e32 v146, v146, v101
	v_sub_f32_e32 v145, v145, v101
	v_sub_f32_e32 v144, v144, v101
	v_sub_f32_e32 v143, v143, v101
	v_sub_f32_e32 v142, v142, v101
	v_sub_f32_e32 v141, v141, v101
	v_sub_f32_e32 v140, v140, v101
	v_sub_f32_e32 v139, v139, v101
	v_sub_f32_e32 v138, v138, v101
	v_sub_f32_e32 v137, v137, v101
	v_sub_f32_e32 v136, v136, v101
	v_sub_f32_e32 v135, v135, v101
	v_sub_f32_e32 v134, v134, v101
	v_sub_f32_e32 v133, v133, v101
	v_sub_f32_e32 v132, v132, v101
	v_sub_f32_e32 v19, v19, v101
	v_sub_f32_e32 v18, v18, v101
	v_sub_f32_e32 v17, v17, v101
	v_sub_f32_e32 v16, v16, v101
	v_sub_f32_e32 v15, v15, v101
	v_sub_f32_e32 v14, v14, v101
	v_sub_f32_e32 v13, v13, v101
	v_sub_f32_e32 v12, v12, v101
	v_sub_f32_e32 v11, v11, v101
	v_sub_f32_e32 v10, v10, v101
	v_sub_f32_e32 v9, v9, v101
	v_sub_f32_e32 v8, v8, v101
	v_sub_f32_e32 v7, v7, v101
	v_sub_f32_e32 v6, v6, v101
	v_sub_f32_e32 v5, v5, v101
	v_sub_f32_e32 v4, v4, v101
	v_mul_f32_e32 v197, v197, v100

; DI float max3f(float a, float b, float c) { float r; asm("v_max3_f32 %0, %1, %2, %3" : "=v"(r) : "v"(a), "v"(b), "v"(c)); return r; }
; DI float swapmax(float m) { auto rr = __builtin_amdgcn_permlane32_swap(__float_as_uint(m), __float_as_uint(m), false, false); return fmaxf(__uint_as_float(rr[0]), __uint_as_float(rr[1])); }
; #define SBAR() __builtin_amdgcn_sched_barrier(0)
; #define PIN(x) asm volatile("" : "+v"(x))
; #define LDV(j_) do { if ((j_) < 4 * NDB) { const lds_cptr a_ = vp + ((j_) % NDB) * 4096 + ((j_) / NDB) * 1024; const s16x4 lo_ = vtr(a_), hi_ = vtr(a_ + 512); \
;             vq[(j_) & 3] = (bf16x8){lo_[0], lo_[1], lo_[2], lo_[3], hi_[0], hi_[1], hi_[2], hi_[3]}; } } while (0)
; #define PVM(j_) o[(j_) % NDB] = MF(vq[(j_) & 3], pw[(j_) / NDB], o[(j_) % NDB])
; template <int KIND> DI void attn_unit(const Params& P, int b, int h, int qb, char* shm, float lam, bool dry = false) {
;     ...
;             PVM(13); rm = max3f(rm, pb1[10], pb1[11]); rm2 = max3f(rm2, pb0[12], pb0[13]); PIN(rm); PIN(rm2); SBAR();
;             PVM(14); rm = max3f(rm, pb0[14], pb0[15]); rm2 = max3f(rm2, pb1[12], pb1[13]); PIN(rm); PIN(rm2); SBAR();
;             PVM(15); rm = max3f(rm, pb1[14], pb1[15]); PIN(rm); SBAR();
;         } else {
;             LDV(7); PVM(4); rm = max3f(pb0[0], pb0[1], pb1[0]); rm2 = max3f(pb0[2], pb0[3], pb1[1]); rm = max3f(rm, pb1[2], pb1[3]); rm2 = max3f(rm2, pb0[4], pb0[5]); PIN(rm); PIN(rm2); SBAR();
;             PVM(5); rm = max3f(rm, pb0[6], pb0[7]); rm2 = max3f(rm2, pb1[4], pb1[5]); rm = max3f(rm, pb1[6], pb1[7]); rm2 = max3f(rm2, pb0[8], pb0[9]); PIN(rm); PIN(rm2); SBAR();
;             PVM(6); rm = max3f(rm, pb0[10], pb0[11]); rm2 = max3f(rm2, pb1[8], pb1[9]); rm = max3f(rm, pb1[10], pb1[11]); rm2 = max3f(rm2, pb0[12], pb0[13]); PIN(rm); PIN(rm2); SBAR();
;             PVM(7); rm = max3f(rm, pb0[14], pb0[15]); rm2 = max3f(rm2, pb1[12], pb1[13]); rm = max3f(rm, pb1[14], pb1[15]); PIN(rm); PIN(rm2); SBAR();
;         }
;     ...
;         rm = swapmax(max3f(rm, rm2, rm2));
.Lat2_nd3:
	ds_read_b64_tr_b16 v[132:133], v190 offset:31744
	ds_read_b64_tr_b16 v[134:135], v190 offset:32256
	v_max3_f32 v116, v116, v110, v111
	v_max3_f32 v117, v117, v92, v93
	s_waitcnt lgkmcnt(4)
	v_mfma_f32_32x32x16_bf16 v[52:67], v[140:143], v[128:131], v[52:67]
	v_max3_f32 v116, v116, v94, v95
	v_max3_f32 v117, v117, v112, v113
	s_waitcnt lgkmcnt(2)
	v_mfma_f32_32x32x16_bf16 v[36:51], v[144:147], v[128:131], v[36:51]
	v_max3_f32 v116, v116, v114, v115
	v_max3_f32 v117, v117, v96, v97
	v_max3_f32 v116, v116, v98, v99
	v_max3_f32 v116, v116, v117, v117
	v_mov_b32_e32 v117, v116
	s_waitcnt lgkmcnt(0)
	v_mfma_f32_32x32x16_bf16 v[20:35], v[132:135], v[128:131], v[20:35]
	s_add_i32 s3, s3, 1
	s_cmp_ge_u32 s3, s18
	v_permlane32_swap_b32_e32 v116, v117
	s_cbranch_scc1 .Lat2_408


	v_max_f32_e32 v116, v116, v117
	v_cmp_lt_f32_e32 vcc, s88, v116
	s_cbranch_vccz .Lat2_408
	v_max_f32_e32 v116, v116, v116
	v_max_f32_e32 v117, 0, v116
	v_exp_f32_e64 v116, -v117
	v_sub_f32_e32 v115, v115, v117
	v_sub_f32_e32 v114, v114, v117
	v_sub_f32_e32 v113, v113, v117
	v_pk_mul_f32 v[82:83], v[82:83], v[116:117] op_sel_hi:[1,0]
	v_pk_mul_f32 v[80:81], v[80:81], v[116:117] op_sel_hi:[1,0]
	v_pk_mul_f32 v[78:79], v[78:79], v[116:117] op_sel_hi:[1,0]
	v_pk_mul_f32 v[76:77], v[76:77], v[116:117] op_sel_hi:[1,0]
	v_pk_mul_f32 v[74:75], v[74:75], v[116:117] op_sel_hi:[1,0]
	v_pk_mul_f32 v[72:73], v[72:73], v[116:117] op_sel_hi:[1,0]
	v_pk_mul_f32 v[70:71], v[70:71], v[116:117] op_sel_hi:[1,0]
	v_pk_mul_f32 v[68:69], v[68:69], v[116:117] op_sel_hi:[1,0]
	v_pk_mul_f32 v[66:67], v[66:67], v[116:117] op_sel_hi:[1,0]
	v_pk_mul_f32 v[64:65], v[64:65], v[116:117] op_sel_hi:[1,0]
	v_pk_mul_f32 v[62:63], v[62:63], v[116:117] op_sel_hi:[1,0]
	v_pk_mul_f32 v[60:61], v[60:61], v[116:117] op_sel_hi:[1,0]
	v_pk_mul_f32 v[58:59], v[58:59], v[116:117] op_sel_hi:[1,0]
	v_pk_mul_f32 v[56:57], v[56:57], v[116:117] op_sel_hi:[1,0]
	v_pk_mul_f32 v[54:55], v[54:55], v[116:117] op_sel_hi:[1,0]
	v_pk_mul_f32 v[52:53], v[52:53], v[116:117] op_sel_hi:[1,0]
	v_pk_mul_f32 v[50:51], v[50:51], v[116:117] op_sel_hi:[1,0]
	v_pk_mul_f32 v[48:49], v[48:49], v[116:117] op_sel_hi:[1,0]
	v_pk_mul_f32 v[46:47], v[46:47], v[116:117] op_sel_hi:[1,0]
	v_pk_mul_f32 v[44:45], v[44:45], v[116:117] op_sel_hi:[1,0]
	v_pk_mul_f32 v[42:43], v[42:43], v[116:117] op_sel_hi:[1,0]
	v_pk_mul_f32 v[40:41], v[40:41], v[116:117] op_sel_hi:[1,0]
	v_pk_mul_f32 v[38:39], v[38:39], v[116:117] op_sel_hi:[1,0]
	v_pk_mul_f32 v[36:37], v[36:37], v[116:117] op_sel_hi:[1,0]
	v_pk_mul_f32 v[34:35], v[34:35], v[116:117] op_sel_hi:[1,0]
	v_pk_mul_f32 v[32:33], v[32:33], v[116:117] op_sel_hi:[1,0]
	v_pk_mul_f32 v[30:31], v[30:31], v[116:117] op_sel_hi:[1,0]
	v_pk_mul_f32 v[28:29], v[28:29], v[116:117] op_sel_hi:[1,0]
	v_pk_mul_f32 v[26:27], v[26:27], v[116:117] op_sel_hi:[1,0]
	v_pk_mul_f32 v[24:25], v[24:25], v[116:117] op_sel_hi:[1,0]
	v_pk_mul_f32 v[22:23], v[22:23], v[116:117] op_sel_hi:[1,0]
	v_pk_mul_f32 v[20:21], v[20:21], v[116:117] op_sel_hi:[1,0]
	v_sub_f32_e32 v112, v112, v117
	v_sub_f32_e32 v111, v111, v117
	v_sub_f32_e32 v110, v110, v117
	v_sub_f32_e32 v109, v109, v117
	v_sub_f32_e32 v108, v108, v117
	v_sub_f32_e32 v107, v107, v117
	v_sub_f32_e32 v106, v106, v117
	v_sub_f32_e32 v105, v105, v117
	v_sub_f32_e32 v104, v104, v117
	v_sub_f32_e32 v103, v103, v117
	v_sub_f32_e32 v102, v102, v117
	v_sub_f32_e32 v101, v101, v117
	v_sub_f32_e32 v100, v100, v117
	v_sub_f32_e32 v99, v99, v117
	v_sub_f32_e32 v98, v98, v117
	v_sub_f32_e32 v97, v97, v117
	v_sub_f32_e32 v96, v96, v117
	v_sub_f32_e32 v95, v95, v117
	v_sub_f32_e32 v94, v94, v117
	v_sub_f32_e32 v93, v93, v117
	v_sub_f32_e32 v92, v92, v117
	v_sub_f32_e32 v91, v91, v117
	v_sub_f32_e32 v90, v90, v117
	v_sub_f32_e32 v89, v89, v117
	v_sub_f32_e32 v88, v88, v117
	v_sub_f32_e32 v87, v87, v117
	v_sub_f32_e32 v86, v86, v117
	v_sub_f32_e32 v85, v85, v117
	v_sub_f32_e32 v84, v84, v117
	v_sub_f32_e32 v19, v19, v117
	v_sub_f32_e32 v18, v18, v117
	v_sub_f32_e32 v17, v17, v117
	v_sub_f32_e32 v16, v16, v117
	v_sub_f32_e32 v15, v15, v117
	v_sub_f32_e32 v14, v14, v117
	v_sub_f32_e32 v13, v13, v117
	v_sub_f32_e32 v12, v12, v117
	v_sub_f32_e32 v11, v11, v117
	v_sub_f32_e32 v10, v10, v117
	v_sub_f32_e32 v9, v9, v117
	v_sub_f32_e32 v8, v8, v117
	v_sub_f32_e32 v7, v7, v117
	v_sub_f32_e32 v6, v6, v117
	v_sub_f32_e32 v5, v5, v117
	v_sub_f32_e32 v4, v4, v117
	v_mul_f32_e32 v197, v197, v116

; DI float max3f(float a, float b, float c) { float r; asm("v_max3_f32 %0, %1, %2, %3" : "=v"(r) : "v"(a), "v"(b), "v"(c)); return r; }
; DI float swapmax(float m) { auto rr = __builtin_amdgcn_permlane32_swap(__float_as_uint(m), __float_as_uint(m), false, false); return fmaxf(__uint_as_float(rr[0]), __uint_as_float(rr[1])); }
; #define SBAR() __builtin_amdgcn_sched_barrier(0)
; #define PIN(x) asm volatile("" : "+v"(x))
; template <int KIND> DI void attn_unit(const Params& P, int b, int h, int qb, char* shm, float lam, bool dry = false) {
;     ...
;         ATT_FIX(pb0, pb1, ATT_TILE(i + 1));
;         float rm, rm2;
;         if (NDB == 4) {
;             LDV(11); PVM(8); rm = max3f(pb0[0], pb0[1], pb1[0]); rm2 = max3f(pb0[2], pb0[3], pb1[1]); PIN(rm); PIN(rm2); SBAR();
;             LDV(12); PVM(9); rm = max3f(rm, pb1[2], pb1[3]); rm2 = max3f(rm2, pb0[4], pb0[5]); PIN(rm); PIN(rm2); SBAR();
;             LDV(13); PVM(10); rm = max3f(rm, pb0[6], pb0[7]); rm2 = max3f(rm2, pb1[4], pb1[5]); PIN(rm); PIN(rm2); SBAR();
;             LDV(14); PVM(11); rm = max3f(rm, pb1[6], pb1[7]); rm2 = max3f(rm2, pb0[8], pb0[9]); PIN(rm); PIN(rm2); SBAR();
;             LDV(15); PVM(12); rm = max3f(rm, pb0[10], pb0[11]); rm2 = max3f(rm2, pb1[8], pb1[9]); PIN(rm); PIN(rm2); SBAR();
;             PVM(13); rm = max3f(rm, pb1[10], pb1[11]); rm2 = max3f(rm2, pb0[12], pb0[13]); PIN(rm); PIN(rm2); SBAR();
;             PVM(14); rm = max3f(rm, pb0[14], pb0[15]); rm2 = max3f(rm2, pb1[12], pb1[13]); PIN(rm); PIN(rm2); SBAR();
;             PVM(15); rm = max3f(rm, pb1[14], pb1[15]); PIN(rm); SBAR();
;         } else {
;             LDV(7); PVM(4); rm = max3f(pb0[0], pb0[1], pb1[0]); rm2 = max3f(pb0[2], pb0[3], pb1[1]); rm = max3f(rm, pb1[2], pb1[3]); rm2 = max3f(rm2, pb0[4], pb0[5]); PIN(rm); PIN(rm2); SBAR();
;             PVM(5); rm = max3f(rm, pb0[6], pb0[7]); rm2 = max3f(rm2, pb1[4], pb1[5]); rm = max3f(rm, pb1[6], pb1[7]); rm2 = max3f(rm2, pb0[8], pb0[9]); PIN(rm); PIN(rm2); SBAR();
;             PVM(6); rm = max3f(rm, pb0[10], pb0[11]); rm2 = max3f(rm2, pb1[8], pb1[9]); rm = max3f(rm, pb1[10], pb1[11]); rm2 = max3f(rm2, pb0[12], pb0[13]); PIN(rm); PIN(rm2); SBAR();
;             PVM(7); rm = max3f(rm, pb0[14], pb0[15]); rm2 = max3f(rm2, pb1[12], pb1[13]); rm = max3f(rm, pb1[14], pb1[15]); PIN(rm); PIN(rm2); SBAR();
;         }
;     ...
;         rm = swapmax(max3f(rm, rm2, rm2));
.LBB0_419:
	s_cmp_lt_i32 s10, s7
	s_cselect_b64 s[10:11], -1, 0
	s_cmp_ge_i32 s20, s6
	s_waitcnt lgkmcnt(4)
	v_mfma_f32_32x32x16_bf16 v[4:19], v[100:103], v[132:135], v[4:19]
	s_cselect_b64 s[12:13], -1, 0
	s_or_b64 vcc, s[10:11], s[12:13]
	v_cndmask_b32_e32 v55, v87, v245, vcc
	v_cndmask_b32_e32 v54, v86, v245, vcc
	v_cndmask_b32_e32 v53, v85, v245, vcc
	v_cndmask_b32_e32 v52, v84, v245, vcc
	ds_read_b64_tr_b16 v[84:85], v0 offset:23552
	ds_read_b64_tr_b16 v[86:87], v0 offset:24064
	v_add_f32_e32 v159, v159, v1
	v_cndmask_b32_e32 v71, v71, v245, vcc
	v_cndmask_b32_e32 v70, v70, v245, vcc
	v_cndmask_b32_e32 v69, v69, v245, vcc
	v_cndmask_b32_e32 v68, v68, v245, vcc
	v_max3_f32 v1, v68, v69, v52
	v_max3_f32 v3, v70, v71, v53
	v_cndmask_b32_e32 v67, v99, v245, vcc
	v_cndmask_b32_e32 v66, v98, v245, vcc
	v_cndmask_b32_e32 v65, v97, v245, vcc
	v_cndmask_b32_e32 v64, v96, v245, vcc
	v_cndmask_b32_e32 v63, v95, v245, vcc
	v_cndmask_b32_e32 v62, v94, v245, vcc
	v_cndmask_b32_e32 v61, v93, v245, vcc
	v_cndmask_b32_e32 v60, v92, v245, vcc
	v_cndmask_b32_e32 v59, v91, v245, vcc
	v_cndmask_b32_e32 v58, v90, v245, vcc
	v_cndmask_b32_e32 v57, v89, v245, vcc
	v_cndmask_b32_e32 v56, v88, v245, vcc
	v_cndmask_b32_e32 v83, v83, v245, vcc
	v_cndmask_b32_e32 v82, v82, v245, vcc
	v_cndmask_b32_e32 v81, v81, v245, vcc
	v_cndmask_b32_e32 v80, v80, v245, vcc
	v_cndmask_b32_e32 v79, v79, v245, vcc
	v_cndmask_b32_e32 v78, v78, v245, vcc
	v_cndmask_b32_e32 v77, v77, v245, vcc
	v_cndmask_b32_e32 v76, v76, v245, vcc
	v_cndmask_b32_e32 v75, v75, v245, vcc
	v_cndmask_b32_e32 v74, v74, v245, vcc
	v_cndmask_b32_e32 v73, v73, v245, vcc
	v_cndmask_b32_e32 v72, v72, v245, vcc
	v_max3_f32 v1, v1, v54, v55
	v_max3_f32 v3, v3, v72, v73
	s_nop 0
	s_waitcnt lgkmcnt(4)
	v_mfma_f32_32x32x16_bf16 v[20:35], v[104:107], v[132:135], v[20:35]
	v_max3_f32 v1, v1, v74, v75
	v_max3_f32 v3, v3, v56, v57
	s_nop 0
	v_max3_f32 v1, v1, v58, v59
	v_max3_f32 v3, v3, v76, v77
	s_nop 0
	s_waitcnt lgkmcnt(2)
	v_mfma_f32_32x32x16_bf16 v[4:19], v[108:111], v[136:139], v[4:19]
	v_max3_f32 v1, v1, v78, v79
	v_max3_f32 v3, v3, v60, v61
	s_nop 0
	v_max3_f32 v1, v1, v62, v63
	v_max3_f32 v3, v3, v80, v81
	s_nop 0
	s_waitcnt lgkmcnt(0)
	v_mfma_f32_32x32x16_bf16 v[20:35], v[84:87], v[136:139], v[20:35]
	v_max3_f32 v1, v1, v82, v83
	v_max3_f32 v3, v3, v64, v65
	s_nop 0
	v_max3_f32 v1, v1, v66, v67
	s_nop 0
	s_nop 0
	v_max3_f32 v1, v1, v3, v3
	s_andn2_b64 vcc, exec, s[0:1]
	v_mov_b32_e32 v3, v1
	s_nop 1
	v_permlane32_swap_b32_e32 v1, v3
	s_cbranch_vccnz .LBB0_422


	v_max_f32_e32 v1, v1, v3
	v_cmp_lt_f32_e32 vcc, s88, v1
	s_cbranch_vccz .LBB0_422
	v_max_f32_e32 v1, v1, v1
	v_max_f32_e32 v1, 0, v1
	v_exp_f32_e64 v84, -v1
	v_sub_f32_e32 v83, v83, v1
	v_sub_f32_e32 v82, v82, v1
	v_sub_f32_e32 v81, v81, v1
	v_pk_mul_f32 v[34:35], v[34:35], v[84:85] op_sel_hi:[1,0]
	v_pk_mul_f32 v[32:33], v[32:33], v[84:85] op_sel_hi:[1,0]
	v_pk_mul_f32 v[30:31], v[30:31], v[84:85] op_sel_hi:[1,0]
	v_pk_mul_f32 v[28:29], v[28:29], v[84:85] op_sel_hi:[1,0]
	v_pk_mul_f32 v[26:27], v[26:27], v[84:85] op_sel_hi:[1,0]
	v_pk_mul_f32 v[24:25], v[24:25], v[84:85] op_sel_hi:[1,0]
	v_pk_mul_f32 v[22:23], v[22:23], v[84:85] op_sel_hi:[1,0]
	v_pk_mul_f32 v[20:21], v[20:21], v[84:85] op_sel_hi:[1,0]
	v_pk_mul_f32 v[18:19], v[18:19], v[84:85] op_sel_hi:[1,0]
	v_pk_mul_f32 v[16:17], v[16:17], v[84:85] op_sel_hi:[1,0]
	v_pk_mul_f32 v[14:15], v[14:15], v[84:85] op_sel_hi:[1,0]
	v_pk_mul_f32 v[12:13], v[12:13], v[84:85] op_sel_hi:[1,0]
	v_pk_mul_f32 v[10:11], v[10:11], v[84:85] op_sel_hi:[1,0]
	v_pk_mul_f32 v[8:9], v[8:9], v[84:85] op_sel_hi:[1,0]
	v_pk_mul_f32 v[6:7], v[6:7], v[84:85] op_sel_hi:[1,0]
	v_pk_mul_f32 v[4:5], v[4:5], v[84:85] op_sel_hi:[1,0]
	v_sub_f32_e32 v80, v80, v1
	v_sub_f32_e32 v79, v79, v1
	v_sub_f32_e32 v78, v78, v1
	v_sub_f32_e32 v77, v77, v1
	v_sub_f32_e32 v76, v76, v1
	v_sub_f32_e32 v75, v75, v1
	v_sub_f32_e32 v74, v74, v1
	v_sub_f32_e32 v73, v73, v1
	v_sub_f32_e32 v72, v72, v1
	v_sub_f32_e32 v71, v71, v1
	v_sub_f32_e32 v70, v70, v1
	v_sub_f32_e32 v69, v69, v1
	v_sub_f32_e32 v68, v68, v1
	v_sub_f32_e32 v67, v67, v1
	v_sub_f32_e32 v66, v66, v1
	v_sub_f32_e32 v65, v65, v1
	v_sub_f32_e32 v64, v64, v1
	v_sub_f32_e32 v63, v63, v1
	v_sub_f32_e32 v62, v62, v1
	v_sub_f32_e32 v61, v61, v1
	v_sub_f32_e32 v60, v60, v1
	v_sub_f32_e32 v59, v59, v1
	v_sub_f32_e32 v58, v58, v1
	v_sub_f32_e32 v57, v57, v1
	v_sub_f32_e32 v56, v56, v1
	v_sub_f32_e32 v55, v55, v1
	v_sub_f32_e32 v54, v54, v1
	v_sub_f32_e32 v53, v53, v1
	v_sub_f32_e32 v52, v52, v1
	v_sub_f32_e32 v51, v51, v1
	v_sub_f32_e32 v50, v50, v1
	v_sub_f32_e32 v49, v49, v1
	v_sub_f32_e32 v48, v48, v1
	v_sub_f32_e32 v47, v47, v1
	v_sub_f32_e32 v46, v46, v1
	v_sub_f32_e32 v45, v45, v1
	v_sub_f32_e32 v44, v44, v1
	v_sub_f32_e32 v43, v43, v1
	v_sub_f32_e32 v42, v42, v1
	v_sub_f32_e32 v41, v41, v1
	v_sub_f32_e32 v40, v40, v1
	v_sub_f32_e32 v39, v39, v1
	v_sub_f32_e32 v38, v38, v1
	v_sub_f32_e32 v37, v37, v1
	v_sub_f32_e32 v36, v36, v1
	v_mul_f32_e32 v159, v159, v84

; DI float max3f(float a, float b, float c) { float r; asm("v_max3_f32 %0, %1, %2, %3" : "=v"(r) : "v"(a), "v"(b), "v"(c)); return r; }
; DI float swapmax(float m) { auto rr = __builtin_amdgcn_permlane32_swap(__float_as_uint(m), __float_as_uint(m), false, false); return fmaxf(__uint_as_float(rr[0]), __uint_as_float(rr[1])); }
; #define SBAR() __builtin_amdgcn_sched_barrier(0)
; #define PIN(x) asm volatile("" : "+v"(x))
; #define LDV(j_) do { if ((j_) < 4 * NDB) { const lds_cptr a_ = vp + ((j_) % NDB) * 4096 + ((j_) / NDB) * 1024; const s16x4 lo_ = vtr(a_), hi_ = vtr(a_ + 512); \
;             vq[(j_) & 3] = (bf16x8){lo_[0], lo_[1], lo_[2], lo_[3], hi_[0], hi_[1], hi_[2], hi_[3]}; } } while (0)
; #define PVM(j_) o[(j_) % NDB] = MF(vq[(j_) & 3], pw[(j_) / NDB], o[(j_) % NDB])
; template <int KIND> DI void attn_unit(const Params& P, int b, int h, int qb, char* shm, float lam, bool dry = false) {
;     ...
;             LDV(7); PVM(4); rm = max3f(pb0[0], pb0[1], pb1[0]); rm2 = max3f(pb0[2], pb0[3], pb1[1]); rm = max3f(rm, pb1[2], pb1[3]); rm2 = max3f(rm2, pb0[4], pb0[5]); PIN(rm); PIN(rm2); SBAR();
;             PVM(5); rm = max3f(rm, pb0[6], pb0[7]); rm2 = max3f(rm2, pb1[4], pb1[5]); rm = max3f(rm, pb1[6], pb1[7]); rm2 = max3f(rm2, pb0[8], pb0[9]); PIN(rm); PIN(rm2); SBAR();
;             PVM(6); rm = max3f(rm, pb0[10], pb0[11]); rm2 = max3f(rm2, pb1[8], pb1[9]); rm = max3f(rm, pb1[10], pb1[11]); rm2 = max3f(rm2, pb0[12], pb0[13]); PIN(rm); PIN(rm2); SBAR();
;             PVM(7); rm = max3f(rm, pb0[14], pb0[15]); rm2 = max3f(rm2, pb1[12], pb1[13]); rm = max3f(rm, pb1[14], pb1[15]); PIN(rm); PIN(rm2); SBAR();
;         }
;     ...
;         rm = swapmax(max3f(rm, rm2, rm2));
.LBB0_433:
	s_cmp_lt_i32 s1, s7
	s_cselect_b64 s[14:15], -1, 0
	s_cmp_gt_i32 s1, s6
	s_waitcnt lgkmcnt(4)
	v_mfma_f32_32x32x16_bf16 v[4:19], v[140:143], v[132:135], v[4:19]
	s_cselect_b64 s[16:17], -1, 0
	s_or_b64 vcc, s[14:15], s[16:17]
	v_add_f32_e32 v159, v159, v68
	v_cndmask_b32_e32 v71, v87, v245, vcc
	v_cndmask_b32_e32 v70, v86, v245, vcc
	v_cndmask_b32_e32 v69, v85, v245, vcc
	v_cndmask_b32_e32 v68, v84, v245, vcc
	ds_read_b64_tr_b16 v[84:85], v3 offset:23552
	ds_read_b64_tr_b16 v[86:87], v3 offset:24064
	v_cndmask_b32_e32 v53, v101, v245, vcc
	v_cndmask_b32_e32 v52, v100, v245, vcc
	v_cndmask_b32_e32 v72, v88, v245, vcc
	v_max3_f32 v3, v68, v69, v52
	v_max3_f32 v88, v70, v71, v53
	v_cndmask_b32_e32 v67, v115, v245, vcc
	v_cndmask_b32_e32 v66, v114, v245, vcc
	v_cndmask_b32_e32 v65, v113, v245, vcc
	v_cndmask_b32_e32 v64, v112, v245, vcc
	v_cndmask_b32_e32 v63, v111, v245, vcc
	v_cndmask_b32_e32 v62, v110, v245, vcc
	v_cndmask_b32_e32 v61, v109, v245, vcc
	v_cndmask_b32_e32 v60, v108, v245, vcc
	v_cndmask_b32_e32 v59, v107, v245, vcc
	v_cndmask_b32_e32 v58, v106, v245, vcc
	v_cndmask_b32_e32 v57, v105, v245, vcc
	v_cndmask_b32_e32 v56, v104, v245, vcc
	v_cndmask_b32_e32 v55, v103, v245, vcc
	v_cndmask_b32_e32 v54, v102, v245, vcc
	v_cndmask_b32_e32 v83, v99, v245, vcc
	v_cndmask_b32_e32 v82, v98, v245, vcc
	v_cndmask_b32_e32 v81, v97, v245, vcc
	v_cndmask_b32_e32 v80, v96, v245, vcc
	v_cndmask_b32_e32 v79, v95, v245, vcc
	v_cndmask_b32_e32 v78, v94, v245, vcc
	v_cndmask_b32_e32 v77, v93, v245, vcc
	v_cndmask_b32_e32 v76, v92, v245, vcc
	v_cndmask_b32_e32 v75, v91, v245, vcc
	v_cndmask_b32_e32 v74, v90, v245, vcc
	v_cndmask_b32_e32 v73, v89, v245, vcc
	v_max3_f32 v3, v3, v54, v55
	v_max3_f32 v88, v88, v72, v73
	s_nop 0
	s_waitcnt lgkmcnt(4)
	v_mfma_f32_32x32x16_bf16 v[20:35], v[144:147], v[132:135], v[20:35]
	v_max3_f32 v3, v3, v74, v75
	v_max3_f32 v88, v88, v56, v57
	s_nop 0
	v_max3_f32 v3, v3, v58, v59
	v_max3_f32 v88, v88, v76, v77
	s_nop 0
	s_waitcnt lgkmcnt(2)
	v_mfma_f32_32x32x16_bf16 v[4:19], v[148:151], v[136:139], v[4:19]
	v_max3_f32 v3, v3, v78, v79
	v_max3_f32 v88, v88, v60, v61
	s_nop 0
	v_max3_f32 v3, v3, v62, v63
	v_max3_f32 v88, v88, v80, v81
	s_nop 0
	s_waitcnt lgkmcnt(0)
	v_mfma_f32_32x32x16_bf16 v[20:35], v[84:87], v[136:139], v[20:35]
	v_max3_f32 v3, v3, v82, v83
	v_max3_f32 v84, v88, v64, v65
	s_nop 0
	v_max3_f32 v3, v3, v66, v67
	s_nop 0
	s_nop 0
	v_max3_f32 v3, v3, v84, v84
	s_cmp_ge_i32 s13, s4
	v_mov_b32_e32 v84, v3
	s_nop 1
	v_permlane32_swap_b32_e32 v3, v84
	s_cbranch_scc1 .LBB0_436


	v_max_f32_e32 v3, v3, v84
	v_cmp_lt_f32_e32 vcc, s88, v3
	s_cbranch_vccz .LBB0_436
	v_max_f32_e32 v3, v3, v3
	v_max_f32_e32 v3, 0, v3
	v_exp_f32_e64 v84, -v3
	v_sub_f32_e32 v83, v83, v3
	v_sub_f32_e32 v82, v82, v3
	v_sub_f32_e32 v81, v81, v3
	v_pk_mul_f32 v[34:35], v[34:35], v[84:85] op_sel_hi:[1,0]
	v_pk_mul_f32 v[32:33], v[32:33], v[84:85] op_sel_hi:[1,0]
	v_pk_mul_f32 v[30:31], v[30:31], v[84:85] op_sel_hi:[1,0]
	v_pk_mul_f32 v[28:29], v[28:29], v[84:85] op_sel_hi:[1,0]
	v_pk_mul_f32 v[26:27], v[26:27], v[84:85] op_sel_hi:[1,0]
	v_pk_mul_f32 v[24:25], v[24:25], v[84:85] op_sel_hi:[1,0]
	v_pk_mul_f32 v[22:23], v[22:23], v[84:85] op_sel_hi:[1,0]
	v_pk_mul_f32 v[20:21], v[20:21], v[84:85] op_sel_hi:[1,0]
	v_pk_mul_f32 v[18:19], v[18:19], v[84:85] op_sel_hi:[1,0]
	v_pk_mul_f32 v[16:17], v[16:17], v[84:85] op_sel_hi:[1,0]
	v_pk_mul_f32 v[14:15], v[14:15], v[84:85] op_sel_hi:[1,0]
	v_pk_mul_f32 v[12:13], v[12:13], v[84:85] op_sel_hi:[1,0]
	v_pk_mul_f32 v[10:11], v[10:11], v[84:85] op_sel_hi:[1,0]
	v_pk_mul_f32 v[8:9], v[8:9], v[84:85] op_sel_hi:[1,0]
	v_pk_mul_f32 v[6:7], v[6:7], v[84:85] op_sel_hi:[1,0]
	v_pk_mul_f32 v[4:5], v[4:5], v[84:85] op_sel_hi:[1,0]
	v_sub_f32_e32 v80, v80, v3
	v_sub_f32_e32 v79, v79, v3
	v_sub_f32_e32 v78, v78, v3
	v_sub_f32_e32 v77, v77, v3
	v_sub_f32_e32 v76, v76, v3
	v_sub_f32_e32 v75, v75, v3
	v_sub_f32_e32 v74, v74, v3
	v_sub_f32_e32 v73, v73, v3
	v_sub_f32_e32 v72, v72, v3
	v_sub_f32_e32 v71, v71, v3
	v_sub_f32_e32 v70, v70, v3
	v_sub_f32_e32 v69, v69, v3
	v_sub_f32_e32 v68, v68, v3
	v_sub_f32_e32 v67, v67, v3
	v_sub_f32_e32 v66, v66, v3
	v_sub_f32_e32 v65, v65, v3
	v_sub_f32_e32 v64, v64, v3
	v_sub_f32_e32 v63, v63, v3
	v_sub_f32_e32 v62, v62, v3
	v_sub_f32_e32 v61, v61, v3
	v_sub_f32_e32 v60, v60, v3
	v_sub_f32_e32 v59, v59, v3
	v_sub_f32_e32 v58, v58, v3
	v_sub_f32_e32 v57, v57, v3
	v_sub_f32_e32 v56, v56, v3
	v_sub_f32_e32 v55, v55, v3
	v_sub_f32_e32 v54, v54, v3
	v_sub_f32_e32 v53, v53, v3
	v_sub_f32_e32 v52, v52, v3
	v_sub_f32_e32 v51, v51, v3
	v_sub_f32_e32 v50, v50, v3
	v_sub_f32_e32 v49, v49, v3
	v_sub_f32_e32 v48, v48, v3
	v_sub_f32_e32 v47, v47, v3
	v_sub_f32_e32 v46, v46, v3
	v_sub_f32_e32 v45, v45, v3
	v_sub_f32_e32 v44, v44, v3
	v_sub_f32_e32 v43, v43, v3
	v_sub_f32_e32 v42, v42, v3
	v_sub_f32_e32 v41, v41, v3
	v_sub_f32_e32 v40, v40, v3
	v_sub_f32_e32 v39, v39, v3
	v_sub_f32_e32 v38, v38, v3
	v_sub_f32_e32 v37, v37, v3
	v_sub_f32_e32 v36, v36, v3
	v_mul_f32_e32 v159, v159, v84
